# EpiRes epilogue row-stat reductions via v_permlane16_swap/v_permlane32_swap instead of ds_bpermute (48 of 64 rows)
# speedup vs baseline: 1.0073x; 1.0073x over previous
.LBB0_656:
	v_and_b32_e32 v121, 64, v162
	v_xor_b32_e32 v120, 16, v162
	v_add_u32_e32 v122, 64, v121
	s_lshl_b32 s10, s94, 8
	v_cmp_lt_i32_e32 vcc, v120, v122
	v_mov_b32_e32 v108, v158
	v_mov_b32_e32 v111, v159
	s_add_i32 s10, s10, s65
	v_cndmask_b32_e32 v120, v162, v120, vcc
	v_lshlrev_b32_e32 v121, 2, v120
	v_add_u32_e32 v110, s10, v108
	s_lshl_b32 s10, s92, 8
	v_xor_b32_e32 v120, 32, v162
	s_or_b32 s10, s10, s68
	v_cmp_lt_i32_e32 vcc, v120, v122
	v_lshl_add_u32 v108, v111, 3, s10
	v_ashrrev_i32_e32 v109, 31, v108
	v_cndmask_b32_e32 v120, v162, v120, vcc
	v_cmp_eq_u32_e32 vcc, 0, v111
	v_ashrrev_i32_e32 v111, 31, v110
	v_lshlrev_b64 v[126:127], 11, v[110:111]
	v_lshl_add_u64 v[126:127], s[44:45], 0, v[126:127]
	v_cvt_pk_f16_f32 v122, v56, v57
	v_cvt_pk_f16_f32 v123, v58, v59
	v_cvt_pk_f16_f32 v124, v60, v61
	v_cvt_pk_f16_f32 v125, v62, v63
	v_lshl_add_u64 v[126:127], v[108:109], 1, v[126:127]
	global_store_dwordx4 v[126:127], v[122:125], off
	v_mul_f32_e32 v169, v56, v56
	v_mul_f32_e32 v171, v57, v57
	v_add_f32_e32 v122, v56, v57
	v_add_f32_e32 v124, v58, v59
	v_mul_f32_e32 v173, v58, v58
	v_mul_f32_e32 v175, v59, v59
	v_cvt_pk_f16_f32 v56, v136, v137
	v_cvt_pk_f16_f32 v57, v138, v139
	v_cvt_pk_f16_f32 v58, v132, v133
	v_cvt_pk_f16_f32 v59, v134, v135
	global_store_dwordx4 v[126:127], v[56:59], off offset:256
	v_add_f32_e32 v164, v60, v61
	v_add_f32_e32 v166, v62, v63
	v_pk_mul_f32 v[56:57], v[134:135], v[134:135]
	v_pk_mul_f32 v[58:59], v[132:133], v[132:133]
	v_mul_f32_e32 v177, v60, v60
	v_mul_f32_e32 v61, v61, v61
	v_mul_f32_e32 v179, v62, v62
	v_mul_f32_e32 v63, v63, v63
	v_pk_mov_b32 v[126:127], v[58:59], v[56:57] op_sel:[1,0]
	v_mov_b32_e32 v59, v57
	v_mov_b32_e32 v168, v136
	v_mov_b32_e32 v170, v137
	v_mov_b32_e32 v172, v138
	v_mov_b32_e32 v174, v139
	v_mov_b32_e32 v176, v132
	v_mov_b32_e32 v60, v133
	v_mov_b32_e32 v178, v134
	v_mov_b32_e32 v62, v135
	v_pk_add_f32 v[56:57], v[126:127], v[58:59]
	v_pk_add_f32 v[58:59], v[168:169], v[170:171]
	v_pk_add_f32 v[126:127], v[172:173], v[174:175]
	v_pk_add_f32 v[60:61], v[176:177], v[60:61]
	v_pk_add_f32 v[62:63], v[178:179], v[62:63]
	v_mul_f32_e32 v123, v136, v136
	v_mul_f32_e32 v125, v137, v137
	v_mul_f32_e32 v165, v138, v138
	v_mul_f32_e32 v167, v139, v139
	v_pk_add_f32 v[58:59], v[58:59], v[126:127]
	v_pk_add_f32 v[60:61], v[60:61], v[62:63]
	v_pk_add_f32 v[56:57], v[56:57], v[56:57] op_sel_hi:[0,1]
	v_pk_add_f32 v[58:59], v[58:59], v[60:61]
	v_pk_add_f32 v[60:61], v[122:123], v[124:125]
	v_pk_add_f32 v[62:63], v[164:165], v[166:167]
	v_mov_b32_e32 v149, v57
	v_pk_add_f32 v[60:61], v[60:61], v[62:63]
	v_lshlrev_b32_e32 v120, 2, v120
	v_pk_add_f32 v[56:57], v[60:61], v[148:149]
	s_lshl_b32 s10, s92, 2
	v_pk_add_f32 v[56:57], v[58:59], v[56:57]
	s_nop 0
	v_mov_b32_e32 v58, v56
	v_mov_b32_e32 v59, v57
	s_nop 1
	v_permlane16_swap_b32 v58, v56
	v_permlane16_swap_b32 v59, v57
	s_nop 0
	s_ashr_i32 s11, s10, 31
	s_or_b64 s[92:93], s[10:11], s[0:1]
	s_nop 0
	v_pk_add_f32 v[56:57], v[56:57], v[58:59]
	s_nop 0
	v_mov_b32_e32 v58, v56
	v_mov_b32_e32 v59, v57
	s_nop 1
	v_permlane32_swap_b32 v58, v56
	v_permlane32_swap_b32 v59, v57
	s_nop 0
	v_pk_add_f32 v[56:57], v[56:57], v[58:59]
	s_and_saveexec_b64 s[46:47], vcc
	s_cbranch_execz .LBB0_658
	v_lshlrev_b64 v[60:61], 7, v[110:111]
	s_waitcnt lgkmcnt(0)
	v_lshl_add_u64 v[58:59], s[62:63], 0, v[60:61]
	v_lshl_add_u64 v[58:59], s[92:93], 3, v[58:59]
	global_store_dwordx2 v[58:59], v[56:57], off
.LBB0_658:
	s_or_b64 exec, exec, s[46:47]
	v_add_u32_e32 v56, 16, v110
	v_ashrrev_i32_e32 v57, 31, v56
	v_lshlrev_b64 v[62:63], 11, v[56:57]
	v_lshl_add_u64 v[62:63], s[44:45], 0, v[62:63]
	s_waitcnt lgkmcnt(0)
	v_cvt_pk_f16_f32 v58, v76, v77
	v_cvt_pk_f16_f32 v59, v78, v79
	v_cvt_pk_f16_f32 v60, v84, v85
	v_cvt_pk_f16_f32 v61, v86, v87
	v_lshl_add_u64 v[62:63], v[108:109], 1, v[62:63]
	global_store_dwordx4 v[62:63], v[58:61], off
	v_add_f32_e32 v122, v76, v77
	v_add_f32_e32 v124, v78, v79
	v_cvt_pk_f16_f32 v58, v128, v129
	v_cvt_pk_f16_f32 v59, v130, v131
	v_cvt_pk_f16_f32 v60, v112, v113
	v_cvt_pk_f16_f32 v61, v114, v115
	global_store_dwordx4 v[62:63], v[58:61], off offset:256
	v_mul_f32_e32 v135, v76, v76
	v_mul_f32_e32 v77, v77, v77
	v_pk_mul_f32 v[58:59], v[114:115], v[114:115]
	v_pk_mul_f32 v[60:61], v[112:113], v[112:113]
	v_mul_f32_e32 v137, v78, v78
	v_mul_f32_e32 v79, v79, v79
	v_pk_mov_b32 v[62:63], v[60:61], v[58:59] op_sel:[1,0]
	v_mov_b32_e32 v61, v59
	v_mov_b32_e32 v134, v128
	v_mov_b32_e32 v76, v129
	v_mov_b32_e32 v136, v130
	v_mov_b32_e32 v78, v131
	v_add_f32_e32 v126, v84, v85
	v_add_f32_e32 v132, v86, v87
	v_mul_f32_e32 v139, v84, v84
	v_mul_f32_e32 v85, v85, v85
	v_mul_f32_e32 v165, v86, v86
	v_mul_f32_e32 v87, v87, v87
	v_pk_add_f32 v[58:59], v[62:63], v[60:61]
	v_pk_add_f32 v[60:61], v[134:135], v[76:77]
	v_pk_add_f32 v[62:63], v[136:137], v[78:79]
	v_mov_b32_e32 v138, v112
	v_mov_b32_e32 v84, v113
	v_mov_b32_e32 v164, v114
	v_mov_b32_e32 v86, v115
	v_pk_add_f32 v[60:61], v[60:61], v[62:63]
	v_pk_add_f32 v[62:63], v[138:139], v[84:85]
	v_pk_add_f32 v[76:77], v[164:165], v[86:87]
	v_mul_f32_e32 v123, v128, v128
	v_mul_f32_e32 v125, v129, v129
	v_mul_f32_e32 v127, v130, v130
	v_mul_f32_e32 v133, v131, v131
	v_pk_add_f32 v[62:63], v[62:63], v[76:77]
	v_pk_add_f32 v[58:59], v[58:59], v[58:59] op_sel_hi:[0,1]
	v_pk_add_f32 v[60:61], v[60:61], v[62:63]
	v_pk_add_f32 v[62:63], v[122:123], v[124:125]
	v_pk_add_f32 v[76:77], v[126:127], v[132:133]
	v_mov_b32_e32 v149, v59
	v_pk_add_f32 v[62:63], v[62:63], v[76:77]
	s_nop 0
	v_pk_add_f32 v[58:59], v[62:63], v[148:149]
	s_nop 0
	v_pk_add_f32 v[58:59], v[60:61], v[58:59]
	s_nop 0
	v_mov_b32_e32 v60, v58
	v_mov_b32_e32 v61, v59
	s_nop 1
	v_permlane16_swap_b32 v60, v58
	v_permlane16_swap_b32 v61, v59
	s_nop 0
	s_nop 0
	v_pk_add_f32 v[58:59], v[58:59], v[60:61]
	s_nop 0
	v_mov_b32_e32 v60, v58
	v_mov_b32_e32 v61, v59
	s_nop 1
	v_permlane32_swap_b32 v60, v58
	v_permlane32_swap_b32 v61, v59
	s_nop 0
	v_pk_add_f32 v[58:59], v[58:59], v[60:61]
	s_and_saveexec_b64 s[46:47], vcc
	s_cbranch_execz .LBB0_660
	v_lshlrev_b64 v[56:57], 7, v[56:57]
	v_lshl_add_u64 v[56:57], s[62:63], 0, v[56:57]
	s_waitcnt lgkmcnt(0)
	v_lshl_add_u64 v[56:57], s[92:93], 3, v[56:57]
	global_store_dwordx2 v[56:57], v[58:59], off
.LBB0_660:
	s_or_b64 exec, exec, s[46:47]
	v_add_u32_e32 v56, 32, v110
	v_ashrrev_i32_e32 v57, 31, v56
	v_lshlrev_b64 v[62:63], 11, v[56:57]
	v_lshl_add_u64 v[62:63], s[44:45], 0, v[62:63]
	v_cvt_pk_f16_f32 v58, v88, v89
	v_cvt_pk_f16_f32 v59, v90, v91
	s_waitcnt lgkmcnt(0)
	v_cvt_pk_f16_f32 v60, v92, v93
	v_cvt_pk_f16_f32 v61, v94, v95
	v_lshl_add_u64 v[62:63], v[108:109], 1, v[62:63]
	global_store_dwordx4 v[62:63], v[58:61], off
	v_add_f32_e32 v76, v88, v89
	v_add_f32_e32 v78, v90, v91
	v_cvt_pk_f16_f32 v58, v116, v117
	v_cvt_pk_f16_f32 v59, v118, v119
	v_cvt_pk_f16_f32 v60, v104, v105
	v_cvt_pk_f16_f32 v61, v106, v107
	global_store_dwordx4 v[62:63], v[58:61], off offset:256
	v_mul_f32_e32 v113, v88, v88
	v_mul_f32_e32 v89, v89, v89
	v_pk_mul_f32 v[58:59], v[106:107], v[106:107]
	v_pk_mul_f32 v[60:61], v[104:105], v[104:105]
	v_mul_f32_e32 v115, v90, v90
	v_mul_f32_e32 v91, v91, v91
	v_pk_mov_b32 v[62:63], v[60:61], v[58:59] op_sel:[1,0]
	v_mov_b32_e32 v61, v59
	v_mov_b32_e32 v112, v116
	v_mov_b32_e32 v88, v117
	v_mov_b32_e32 v114, v118
	v_mov_b32_e32 v90, v119
	v_add_f32_e32 v84, v92, v93
	v_add_f32_e32 v86, v94, v95
	v_mul_f32_e32 v123, v92, v92
	v_mul_f32_e32 v93, v93, v93
	v_mul_f32_e32 v125, v94, v94
	v_mul_f32_e32 v95, v95, v95
	v_pk_add_f32 v[58:59], v[62:63], v[60:61]
	v_pk_add_f32 v[60:61], v[112:113], v[88:89]
	v_pk_add_f32 v[62:63], v[114:115], v[90:91]
	v_mov_b32_e32 v122, v104
	v_mov_b32_e32 v92, v105
	v_mov_b32_e32 v124, v106
	v_mov_b32_e32 v94, v107
	v_pk_add_f32 v[60:61], v[60:61], v[62:63]
	v_pk_add_f32 v[62:63], v[122:123], v[92:93]
	v_pk_add_f32 v[88:89], v[124:125], v[94:95]
	v_mul_f32_e32 v77, v116, v116
	v_mul_f32_e32 v79, v117, v117
	v_mul_f32_e32 v85, v118, v118
	v_mul_f32_e32 v87, v119, v119
	v_pk_add_f32 v[62:63], v[62:63], v[88:89]
	v_pk_add_f32 v[58:59], v[58:59], v[58:59] op_sel_hi:[0,1]
	v_pk_add_f32 v[60:61], v[60:61], v[62:63]
	v_pk_add_f32 v[62:63], v[76:77], v[78:79]
	v_pk_add_f32 v[76:77], v[84:85], v[86:87]
	v_mov_b32_e32 v149, v59
	v_pk_add_f32 v[62:63], v[62:63], v[76:77]
	s_nop 0
	v_pk_add_f32 v[58:59], v[62:63], v[148:149]
	s_nop 0
	v_pk_add_f32 v[58:59], v[60:61], v[58:59]
	s_nop 0
	v_mov_b32_e32 v60, v58
	v_mov_b32_e32 v61, v59
	s_nop 1
	v_permlane16_swap_b32 v60, v58
	v_permlane16_swap_b32 v61, v59
	s_nop 0
	s_nop 0
	v_pk_add_f32 v[58:59], v[58:59], v[60:61]
	s_nop 0
	v_mov_b32_e32 v60, v58
	v_mov_b32_e32 v61, v59
	s_nop 1
	v_permlane32_swap_b32 v60, v58
	v_permlane32_swap_b32 v61, v59
	s_nop 0
	v_pk_add_f32 v[58:59], v[58:59], v[60:61]
	s_and_saveexec_b64 s[46:47], vcc
	s_cbranch_execz .LBB0_662
	v_lshlrev_b64 v[56:57], 7, v[56:57]
	v_lshl_add_u64 v[56:57], s[62:63], 0, v[56:57]
	s_waitcnt lgkmcnt(0)
	v_lshl_add_u64 v[56:57], s[92:93], 3, v[56:57]
	global_store_dwordx2 v[56:57], v[58:59], off
.LBB0_662:
	s_or_b64 exec, exec, s[46:47]
	v_add_u32_e32 v56, 48, v110
	v_ashrrev_i32_e32 v57, 31, v56
	v_lshlrev_b64 v[62:63], 11, v[56:57]
	v_lshl_add_u64 v[62:63], s[44:45], 0, v[62:63]
	v_cvt_pk_f16_f32 v58, v96, v97
	v_cvt_pk_f16_f32 v59, v98, v99
	s_waitcnt lgkmcnt(0)
	v_cvt_pk_f16_f32 v60, v100, v101
	v_cvt_pk_f16_f32 v61, v102, v103
	v_lshl_add_u64 v[62:63], v[108:109], 1, v[62:63]
	global_store_dwordx4 v[62:63], v[58:61], off
	v_mul_f32_e32 v89, v96, v96
	v_mul_f32_e32 v91, v97, v97
	v_cvt_pk_f16_f32 v58, v68, v69
	v_cvt_pk_f16_f32 v59, v70, v71
	v_cvt_pk_f16_f32 v60, v64, v65
	v_cvt_pk_f16_f32 v61, v66, v67
	global_store_dwordx4 v[62:63], v[58:61], off offset:256
	v_mul_f32_e32 v93, v98, v98
	v_mul_f32_e32 v95, v99, v99
	v_pk_mul_f32 v[58:59], v[66:67], v[66:67]
	v_pk_mul_f32 v[60:61], v[64:65], v[64:65]
	v_mov_b32_e32 v88, v68
	v_pk_mov_b32 v[62:63], v[60:61], v[58:59] op_sel:[1,0]
	v_mov_b32_e32 v61, v59
	v_mov_b32_e32 v90, v69
	v_mov_b32_e32 v92, v70
	v_mov_b32_e32 v94, v71
	v_add_f32_e32 v76, v96, v97
	v_add_f32_e32 v78, v98, v99
	v_add_f32_e32 v84, v100, v101
	v_add_f32_e32 v86, v102, v103
	v_mul_f32_e32 v97, v100, v100
	v_mul_f32_e32 v99, v101, v101
	v_mul_f32_e32 v101, v102, v102
	v_mul_f32_e32 v103, v103, v103
	v_pk_add_f32 v[58:59], v[62:63], v[60:61]
	v_pk_add_f32 v[60:61], v[88:89], v[90:91]
	v_pk_add_f32 v[62:63], v[92:93], v[94:95]
	v_mov_b32_e32 v96, v64
	v_mov_b32_e32 v98, v65
	v_mov_b32_e32 v100, v66
	v_mov_b32_e32 v102, v67
	v_pk_add_f32 v[60:61], v[60:61], v[62:63]
	v_pk_add_f32 v[62:63], v[96:97], v[98:99]
	v_pk_add_f32 v[64:65], v[100:101], v[102:103]
	v_mul_f32_e32 v77, v68, v68
	v_mul_f32_e32 v79, v69, v69
	v_mul_f32_e32 v85, v70, v70
	v_mul_f32_e32 v87, v71, v71
	v_pk_add_f32 v[62:63], v[62:63], v[64:65]
	v_pk_add_f32 v[58:59], v[58:59], v[58:59] op_sel_hi:[0,1]
	v_pk_add_f32 v[60:61], v[60:61], v[62:63]
	v_pk_add_f32 v[62:63], v[76:77], v[78:79]
	v_pk_add_f32 v[64:65], v[84:85], v[86:87]
	v_mov_b32_e32 v149, v59
	v_pk_add_f32 v[62:63], v[62:63], v[64:65]
	s_nop 0
	v_pk_add_f32 v[58:59], v[62:63], v[148:149]
	s_nop 0
	v_pk_add_f32 v[58:59], v[60:61], v[58:59]
	s_nop 0
	v_mov_b32_e32 v60, v58
	v_mov_b32_e32 v61, v59
	s_nop 1
	v_permlane16_swap_b32 v60, v58
	v_permlane16_swap_b32 v61, v59
	s_nop 0
	s_nop 0
	v_pk_add_f32 v[58:59], v[58:59], v[60:61]
	s_nop 0
	v_mov_b32_e32 v60, v58
	v_mov_b32_e32 v61, v59
	s_nop 1
	v_permlane32_swap_b32 v60, v58
	v_permlane32_swap_b32 v61, v59
	s_nop 0
	v_pk_add_f32 v[58:59], v[58:59], v[60:61]
	s_and_saveexec_b64 s[46:47], vcc
	s_cbranch_execz .LBB0_664
	v_lshlrev_b64 v[56:57], 7, v[56:57]
	v_lshl_add_u64 v[56:57], s[62:63], 0, v[56:57]
	s_waitcnt lgkmcnt(0)
	v_lshl_add_u64 v[56:57], s[92:93], 3, v[56:57]
	global_store_dwordx2 v[56:57], v[58:59], off
.LBB0_664:
	s_or_b64 exec, exec, s[46:47]
	v_add_u32_e32 v56, 0x80, v110
	v_ashrrev_i32_e32 v57, 31, v56
	v_lshlrev_b64 v[62:63], 11, v[56:57]
	v_lshl_add_u64 v[62:63], s[44:45], 0, v[62:63]
	v_cvt_pk_f16_f32 v58, v80, v81
	v_cvt_pk_f16_f32 v59, v82, v83
	s_waitcnt lgkmcnt(0)
	v_cvt_pk_f16_f32 v60, v72, v73
	v_cvt_pk_f16_f32 v61, v74, v75
	v_lshl_add_u64 v[62:63], v[108:109], 1, v[62:63]
	global_store_dwordx4 v[62:63], v[58:61], off
	v_add_f32_e32 v64, v80, v81
	v_add_f32_e32 v66, v82, v83
	v_cvt_pk_f16_f32 v58, v44, v45
	v_cvt_pk_f16_f32 v59, v46, v47
	v_cvt_pk_f16_f32 v60, v40, v41
	v_cvt_pk_f16_f32 v61, v42, v43
	v_add_f32_e32 v68, v72, v73
	v_add_f32_e32 v70, v74, v75
	v_mul_f32_e32 v77, v80, v80
	v_mul_f32_e32 v79, v81, v81
	v_mul_f32_e32 v81, v82, v82
	v_mul_f32_e32 v83, v83, v83
	v_mul_f32_e32 v85, v72, v72
	v_mul_f32_e32 v73, v73, v73
	v_mul_f32_e32 v87, v74, v74
	v_mul_f32_e32 v75, v75, v75
	global_store_dwordx4 v[62:63], v[58:61], off offset:256
	v_mov_b32_e32 v76, v44
	v_mov_b32_e32 v78, v45
	v_pk_mul_f32 v[58:59], v[42:43], v[42:43]
	v_pk_mul_f32 v[60:61], v[40:41], v[40:41]
	v_mov_b32_e32 v80, v46
	v_mov_b32_e32 v82, v47
	v_mov_b32_e32 v84, v40
	v_mov_b32_e32 v72, v41
	v_mov_b32_e32 v86, v42
	v_mov_b32_e32 v74, v43
	v_mul_f32_e32 v65, v44, v44
	v_mul_f32_e32 v67, v45, v45
	v_mul_f32_e32 v69, v46, v46
	v_mul_f32_e32 v71, v47, v47
	v_pk_mov_b32 v[62:63], v[60:61], v[58:59] op_sel:[1,0]
	v_mov_b32_e32 v61, v59
	v_pk_add_f32 v[44:45], v[76:77], v[78:79]
	v_pk_add_f32 v[46:47], v[80:81], v[82:83]
	v_pk_add_f32 v[40:41], v[84:85], v[72:73]
	v_pk_add_f32 v[42:43], v[86:87], v[74:75]
	v_pk_add_f32 v[58:59], v[62:63], v[60:61]
	v_pk_add_f32 v[44:45], v[44:45], v[46:47]
	v_pk_add_f32 v[40:41], v[40:41], v[42:43]
	v_pk_add_f32 v[58:59], v[58:59], v[58:59] op_sel_hi:[0,1]
	v_pk_add_f32 v[40:41], v[44:45], v[40:41]
	v_pk_add_f32 v[42:43], v[64:65], v[66:67]
	v_pk_add_f32 v[44:45], v[68:69], v[70:71]
	v_mov_b32_e32 v149, v59
	v_pk_add_f32 v[42:43], v[42:43], v[44:45]
	s_nop 0
	v_pk_add_f32 v[42:43], v[42:43], v[148:149]
	s_nop 0
	v_pk_add_f32 v[40:41], v[40:41], v[42:43]
	s_nop 0
	v_mov_b32_e32 v42, v40
	v_mov_b32_e32 v43, v41
	s_nop 1
	v_permlane16_swap_b32 v42, v40
	v_permlane16_swap_b32 v43, v41
	s_nop 0
	s_nop 0
	v_pk_add_f32 v[40:41], v[40:41], v[42:43]
	s_nop 0
	v_mov_b32_e32 v42, v40
	v_mov_b32_e32 v43, v41
	s_nop 1
	v_permlane32_swap_b32 v42, v40
	v_permlane32_swap_b32 v43, v41
	s_nop 0
	v_pk_add_f32 v[40:41], v[40:41], v[42:43]
	s_and_saveexec_b64 s[46:47], vcc
	s_cbranch_execz .LBB0_666
	v_lshlrev_b64 v[44:45], 7, v[56:57]
	s_waitcnt lgkmcnt(0)
	v_lshl_add_u64 v[42:43], s[62:63], 0, v[44:45]
	v_lshl_add_u64 v[42:43], s[92:93], 3, v[42:43]
	global_store_dwordx2 v[42:43], v[40:41], off
.LBB0_666:
	s_or_b64 exec, exec, s[46:47]
	v_add_u32_e32 v40, 0x90, v110
	v_ashrrev_i32_e32 v41, 31, v40
	v_lshlrev_b64 v[46:47], 11, v[40:41]
	v_lshl_add_u64 v[46:47], s[44:45], 0, v[46:47]
	s_waitcnt lgkmcnt(0)
	v_cvt_pk_f16_f32 v42, v52, v53
	v_cvt_pk_f16_f32 v43, v54, v55
	v_cvt_pk_f16_f32 v44, v48, v49
	v_cvt_pk_f16_f32 v45, v50, v51
	v_lshl_add_u64 v[46:47], v[108:109], 1, v[46:47]
	global_store_dwordx4 v[46:47], v[42:45], off
	v_add_f32_e32 v56, v52, v53
	v_add_f32_e32 v58, v54, v55
	v_cvt_pk_f16_f32 v42, v28, v29
	v_cvt_pk_f16_f32 v43, v30, v31
	v_cvt_pk_f16_f32 v44, v24, v25
	v_cvt_pk_f16_f32 v45, v26, v27
	v_add_f32_e32 v60, v48, v49
	v_add_f32_e32 v62, v50, v51
	v_mul_f32_e32 v65, v52, v52
	v_mul_f32_e32 v53, v53, v53
	v_mul_f32_e32 v67, v54, v54
	v_mul_f32_e32 v55, v55, v55
	v_mul_f32_e32 v69, v48, v48
	v_mul_f32_e32 v49, v49, v49
	v_mul_f32_e32 v71, v50, v50
	v_mul_f32_e32 v51, v51, v51
	global_store_dwordx4 v[46:47], v[42:45], off offset:256
	v_mov_b32_e32 v64, v28
	v_mov_b32_e32 v52, v29
	v_pk_mul_f32 v[42:43], v[26:27], v[26:27]
	v_pk_mul_f32 v[44:45], v[24:25], v[24:25]
	v_mov_b32_e32 v66, v30
	v_mov_b32_e32 v54, v31
	v_mov_b32_e32 v68, v24
	v_mov_b32_e32 v48, v25
	v_mov_b32_e32 v70, v26
	v_mov_b32_e32 v50, v27
	v_mul_f32_e32 v57, v28, v28
	v_mul_f32_e32 v59, v29, v29
	v_mul_f32_e32 v61, v30, v30
	v_mul_f32_e32 v63, v31, v31
	v_pk_mov_b32 v[46:47], v[44:45], v[42:43] op_sel:[1,0]
	v_mov_b32_e32 v45, v43
	v_pk_add_f32 v[28:29], v[64:65], v[52:53]
	v_pk_add_f32 v[30:31], v[66:67], v[54:55]
	v_pk_add_f32 v[24:25], v[68:69], v[48:49]
	v_pk_add_f32 v[26:27], v[70:71], v[50:51]
	v_pk_add_f32 v[42:43], v[46:47], v[44:45]
	v_pk_add_f32 v[28:29], v[28:29], v[30:31]
	v_pk_add_f32 v[24:25], v[24:25], v[26:27]
	v_pk_add_f32 v[42:43], v[42:43], v[42:43] op_sel_hi:[0,1]
	v_pk_add_f32 v[24:25], v[28:29], v[24:25]
	v_pk_add_f32 v[26:27], v[56:57], v[58:59]
	v_pk_add_f32 v[28:29], v[60:61], v[62:63]
	v_mov_b32_e32 v149, v43
	v_pk_add_f32 v[26:27], v[26:27], v[28:29]
	s_nop 0
	v_pk_add_f32 v[26:27], v[26:27], v[148:149]
	s_nop 0
	v_pk_add_f32 v[24:25], v[24:25], v[26:27]
	s_nop 0
	v_mov_b32_e32 v26, v24
	v_mov_b32_e32 v27, v25
	s_nop 1
	v_permlane16_swap_b32 v26, v24
	v_permlane16_swap_b32 v27, v25
	s_nop 0
	s_nop 0
	v_pk_add_f32 v[24:25], v[24:25], v[26:27]
	s_nop 0
	v_mov_b32_e32 v26, v24
	v_mov_b32_e32 v27, v25
	s_nop 1
	v_permlane32_swap_b32 v26, v24
	v_permlane32_swap_b32 v27, v25
	s_nop 0
	v_pk_add_f32 v[24:25], v[24:25], v[26:27]
	s_and_saveexec_b64 s[46:47], vcc
	s_cbranch_execz .LBB0_668
	v_lshlrev_b64 v[28:29], 7, v[40:41]
	s_waitcnt lgkmcnt(0)
	v_lshl_add_u64 v[26:27], s[62:63], 0, v[28:29]
	v_lshl_add_u64 v[26:27], s[92:93], 3, v[26:27]
	global_store_dwordx2 v[26:27], v[24:25], off
.LBB0_668:
	s_or_b64 exec, exec, s[46:47]
	v_add_u32_e32 v24, 0xa0, v110
	v_ashrrev_i32_e32 v25, 31, v24
	v_lshlrev_b64 v[30:31], 11, v[24:25]
	v_lshl_add_u64 v[30:31], s[44:45], 0, v[30:31]
	s_waitcnt lgkmcnt(0)
	v_cvt_pk_f16_f32 v26, v36, v37
	v_cvt_pk_f16_f32 v27, v38, v39
	v_cvt_pk_f16_f32 v28, v32, v33
	v_cvt_pk_f16_f32 v29, v34, v35
	v_lshl_add_u64 v[30:31], v[108:109], 1, v[30:31]
	global_store_dwordx4 v[30:31], v[26:29], off
	v_add_f32_e32 v40, v36, v37
	v_add_f32_e32 v42, v38, v39
	v_cvt_pk_f16_f32 v26, v12, v13
	v_cvt_pk_f16_f32 v27, v14, v15
	v_cvt_pk_f16_f32 v28, v8, v9
	v_cvt_pk_f16_f32 v29, v10, v11
	v_add_f32_e32 v44, v32, v33
	v_add_f32_e32 v46, v34, v35
	v_mul_f32_e32 v49, v36, v36
	v_mul_f32_e32 v37, v37, v37
	v_mul_f32_e32 v51, v38, v38
	v_mul_f32_e32 v39, v39, v39
	v_mul_f32_e32 v53, v32, v32
	v_mul_f32_e32 v33, v33, v33
	v_mul_f32_e32 v55, v34, v34
	v_mul_f32_e32 v35, v35, v35
	global_store_dwordx4 v[30:31], v[26:29], off offset:256
	v_mov_b32_e32 v48, v12
	v_mov_b32_e32 v36, v13
	v_pk_mul_f32 v[26:27], v[10:11], v[10:11]
	v_pk_mul_f32 v[28:29], v[8:9], v[8:9]
	v_mov_b32_e32 v50, v14
	v_mov_b32_e32 v38, v15
	v_mov_b32_e32 v52, v8
	v_mov_b32_e32 v32, v9
	v_mov_b32_e32 v54, v10
	v_mov_b32_e32 v34, v11
	v_mul_f32_e32 v41, v12, v12
	v_mul_f32_e32 v43, v13, v13
	v_mul_f32_e32 v45, v14, v14
	v_mul_f32_e32 v47, v15, v15
	v_pk_mov_b32 v[30:31], v[28:29], v[26:27] op_sel:[1,0]
	v_mov_b32_e32 v29, v27
	v_pk_add_f32 v[12:13], v[48:49], v[36:37]
	v_pk_add_f32 v[14:15], v[50:51], v[38:39]
	v_pk_add_f32 v[8:9], v[52:53], v[32:33]
	v_pk_add_f32 v[10:11], v[54:55], v[34:35]
	v_pk_add_f32 v[26:27], v[30:31], v[28:29]
	v_pk_add_f32 v[12:13], v[12:13], v[14:15]
	v_pk_add_f32 v[8:9], v[8:9], v[10:11]
	v_pk_add_f32 v[26:27], v[26:27], v[26:27] op_sel_hi:[0,1]
	v_pk_add_f32 v[8:9], v[12:13], v[8:9]
	v_pk_add_f32 v[10:11], v[40:41], v[42:43]
	v_pk_add_f32 v[12:13], v[44:45], v[46:47]
	v_mov_b32_e32 v149, v27
	v_pk_add_f32 v[10:11], v[10:11], v[12:13]
	s_nop 0
	v_pk_add_f32 v[10:11], v[10:11], v[148:149]
	s_nop 0
	v_pk_add_f32 v[8:9], v[8:9], v[10:11]
	s_nop 0
	v_mov_b32_e32 v10, v8
	v_mov_b32_e32 v11, v9
	s_nop 1
	v_permlane16_swap_b32 v10, v8
	v_permlane16_swap_b32 v11, v9
	s_nop 0
	s_nop 0
	v_pk_add_f32 v[8:9], v[8:9], v[10:11]
	s_nop 0
	v_mov_b32_e32 v10, v8
	v_mov_b32_e32 v11, v9
	s_nop 1
	v_permlane32_swap_b32 v10, v8
	v_permlane32_swap_b32 v11, v9
	s_nop 0
	v_pk_add_f32 v[8:9], v[8:9], v[10:11]
	s_and_saveexec_b64 s[46:47], vcc
	s_cbranch_execz .LBB0_670
	v_lshlrev_b64 v[12:13], 7, v[24:25]
	s_waitcnt lgkmcnt(0)
	v_lshl_add_u64 v[10:11], s[62:63], 0, v[12:13]
	v_lshl_add_u64 v[10:11], s[92:93], 3, v[10:11]
	global_store_dwordx2 v[10:11], v[8:9], off
.LBB0_670:
	s_or_b64 exec, exec, s[46:47]
	v_add_u32_e32 v8, 0xb0, v110
	v_ashrrev_i32_e32 v9, 31, v8
	v_lshlrev_b64 v[14:15], 11, v[8:9]
	v_lshl_add_u64 v[14:15], s[44:45], 0, v[14:15]
	s_waitcnt lgkmcnt(0)
	v_cvt_pk_f16_f32 v10, v20, v21
	v_cvt_pk_f16_f32 v11, v22, v23
	v_cvt_pk_f16_f32 v12, v16, v17
	v_cvt_pk_f16_f32 v13, v18, v19
	v_lshl_add_u64 v[14:15], v[108:109], 1, v[14:15]
	global_store_dwordx4 v[14:15], v[10:13], off
	v_add_f32_e32 v24, v20, v21
	v_add_f32_e32 v26, v22, v23
	v_cvt_pk_f16_f32 v10, v4, v5
	v_cvt_pk_f16_f32 v11, v6, v7
	v_cvt_pk_f16_f32 v12, v0, v1
	v_cvt_pk_f16_f32 v13, v2, v3
	v_add_f32_e32 v28, v16, v17
	v_add_f32_e32 v30, v18, v19
	v_mul_f32_e32 v33, v20, v20
	v_mul_f32_e32 v21, v21, v21
	v_mul_f32_e32 v35, v22, v22
	v_mul_f32_e32 v23, v23, v23
	v_mul_f32_e32 v37, v16, v16
	v_mul_f32_e32 v17, v17, v17
	v_mul_f32_e32 v39, v18, v18
	v_mul_f32_e32 v19, v19, v19
	global_store_dwordx4 v[14:15], v[10:13], off offset:256
	v_mov_b32_e32 v32, v4
	v_mov_b32_e32 v20, v5
	v_pk_mul_f32 v[10:11], v[2:3], v[2:3]
	v_pk_mul_f32 v[12:13], v[0:1], v[0:1]
	v_mov_b32_e32 v34, v6
	v_mov_b32_e32 v22, v7
	v_mov_b32_e32 v36, v0
	v_mov_b32_e32 v16, v1
	v_mov_b32_e32 v38, v2
	v_mov_b32_e32 v18, v3
	v_mul_f32_e32 v25, v4, v4
	v_mul_f32_e32 v27, v5, v5
	v_mul_f32_e32 v29, v6, v6
	v_mul_f32_e32 v31, v7, v7
	v_pk_mov_b32 v[14:15], v[12:13], v[10:11] op_sel:[1,0]
	v_mov_b32_e32 v13, v11
	v_pk_add_f32 v[4:5], v[32:33], v[20:21]
	v_pk_add_f32 v[6:7], v[34:35], v[22:23]
	v_pk_add_f32 v[0:1], v[36:37], v[16:17]
	v_pk_add_f32 v[2:3], v[38:39], v[18:19]
	v_pk_add_f32 v[10:11], v[14:15], v[12:13]
	v_pk_add_f32 v[4:5], v[4:5], v[6:7]
	v_pk_add_f32 v[0:1], v[0:1], v[2:3]
	v_pk_add_f32 v[10:11], v[10:11], v[10:11] op_sel_hi:[0,1]
	v_pk_add_f32 v[0:1], v[4:5], v[0:1]
	v_pk_add_f32 v[2:3], v[24:25], v[26:27]
	v_pk_add_f32 v[4:5], v[28:29], v[30:31]
	v_mov_b32_e32 v149, v11
	v_pk_add_f32 v[2:3], v[2:3], v[4:5]
	s_nop 0
	v_pk_add_f32 v[2:3], v[2:3], v[148:149]
	s_nop 0
	v_pk_add_f32 v[0:1], v[0:1], v[2:3]
	s_nop 0
	v_mov_b32_e32 v2, v0
	v_mov_b32_e32 v3, v1
	s_nop 1
	v_permlane16_swap_b32 v2, v0
	v_permlane16_swap_b32 v3, v1
	s_nop 0
	s_nop 0
	v_pk_add_f32 v[0:1], v[0:1], v[2:3]
	s_nop 0
	v_mov_b32_e32 v2, v0
	v_mov_b32_e32 v3, v1
	s_nop 1
	v_permlane32_swap_b32 v2, v0
	v_permlane32_swap_b32 v3, v1
	s_nop 0
	v_pk_add_f32 v[0:1], v[0:1], v[2:3]
	s_and_saveexec_b64 s[46:47], vcc
	s_cbranch_execz .LBB0_672
	v_lshlrev_b64 v[4:5], 7, v[8:9]
	s_waitcnt lgkmcnt(0)
	v_lshl_add_u64 v[2:3], s[62:63], 0, v[4:5]
	v_lshl_add_u64 v[2:3], s[92:93], 3, v[2:3]
	global_store_dwordx2 v[2:3], v[0:1], off

.LBB0_833:
	s_lshl_b32 s40, s80, 8
	v_mov_b32_e32 v137, v153
	v_mov_b32_e32 v149, v151
	s_add_i32 s40, s40, s13
	v_cvt_pk_f16_f32 v162, v64, v65
	v_add_u32_e32 v148, s40, v137
	s_lshl_b32 s40, s79, 8
	s_or_b32 s40, s40, s66
	v_lshl_add_u32 v146, v149, 3, s40
	v_cmp_eq_u32_e32 vcc, 0, v149
	v_ashrrev_i32_e32 v149, 31, v148
	v_lshlrev_b64 v[166:167], 11, v[148:149]
	v_ashrrev_i32_e32 v147, 31, v146
	v_lshl_add_u64 v[166:167], s[44:45], 0, v[166:167]
	v_cvt_pk_f16_f32 v163, v66, v67
	v_cvt_pk_f16_f32 v164, v68, v69
	v_cvt_pk_f16_f32 v165, v70, v71
	v_lshl_add_u64 v[166:167], v[146:147], 1, v[166:167]
	global_store_dwordx4 v[166:167], v[162:165], off
	v_mul_f32_e32 v173, v64, v64
	v_mul_f32_e32 v175, v65, v65
	v_add_f32_e32 v162, v64, v65
	v_add_f32_e32 v164, v66, v67
	v_mul_f32_e32 v177, v66, v66
	v_mul_f32_e32 v179, v67, v67
	v_cvt_pk_f16_f32 v64, v120, v121
	v_cvt_pk_f16_f32 v65, v122, v123
	v_cvt_pk_f16_f32 v66, v124, v125
	v_cvt_pk_f16_f32 v67, v126, v127
	global_store_dwordx4 v[166:167], v[64:67], off offset:256
	v_add_f32_e32 v168, v68, v69
	v_add_f32_e32 v170, v70, v71
	v_pk_mul_f32 v[64:65], v[126:127], v[126:127]
	v_pk_mul_f32 v[66:67], v[124:125], v[124:125]
	v_mul_f32_e32 v181, v68, v68
	v_mul_f32_e32 v69, v69, v69
	v_mul_f32_e32 v183, v70, v70
	v_mul_f32_e32 v71, v71, v71
	v_pk_mov_b32 v[166:167], v[66:67], v[64:65] op_sel:[1,0]
	v_mov_b32_e32 v67, v65
	v_mov_b32_e32 v172, v120
	v_mov_b32_e32 v174, v121
	v_mov_b32_e32 v176, v122
	v_mov_b32_e32 v178, v123
	v_mov_b32_e32 v180, v124
	v_mov_b32_e32 v68, v125
	v_mov_b32_e32 v182, v126
	v_mov_b32_e32 v70, v127
	v_mul_f32_e32 v163, v120, v120
	v_mul_f32_e32 v165, v121, v121
	v_pk_add_f32 v[64:65], v[166:167], v[66:67]
	v_pk_add_f32 v[66:67], v[172:173], v[174:175]
	v_pk_add_f32 v[120:121], v[176:177], v[178:179]
	v_pk_add_f32 v[68:69], v[180:181], v[68:69]
	v_pk_add_f32 v[70:71], v[182:183], v[70:71]
	v_mul_f32_e32 v169, v122, v122
	v_mul_f32_e32 v171, v123, v123
	v_pk_add_f32 v[66:67], v[66:67], v[120:121]
	v_pk_add_f32 v[68:69], v[68:69], v[70:71]
	v_pk_add_f32 v[64:65], v[64:65], v[64:65] op_sel_hi:[0,1]
	v_pk_add_f32 v[66:67], v[66:67], v[68:69]
	v_pk_add_f32 v[68:69], v[162:163], v[164:165]
	v_pk_add_f32 v[70:71], v[168:169], v[170:171]
	v_mov_b32_e32 v137, v65
	v_pk_add_f32 v[68:69], v[68:69], v[70:71]
	s_lshl_b32 s40, s79, 2
	v_pk_add_f32 v[64:65], v[68:69], v[136:137]
	s_ashr_i32 s41, s40, 31
	v_pk_add_f32 v[64:65], v[66:67], v[64:65]
	s_nop 0
	v_mov_b32_e32 v66, v64
	v_mov_b32_e32 v67, v65
	s_nop 1
	v_permlane16_swap_b32 v66, v64
	v_permlane16_swap_b32 v67, v65
	s_nop 0
	s_or_b64 s[40:41], s[40:41], s[0:1]
	s_nop 0
	v_pk_add_f32 v[64:65], v[64:65], v[66:67]
	s_nop 0
	v_mov_b32_e32 v66, v64
	v_mov_b32_e32 v67, v65
	s_nop 1
	v_permlane32_swap_b32 v66, v64
	v_permlane32_swap_b32 v67, v65
	s_nop 0
	v_pk_add_f32 v[64:65], v[64:65], v[66:67]
	s_and_saveexec_b64 s[46:47], vcc
	s_cbranch_execz .LBB0_835
	v_lshlrev_b64 v[68:69], 7, v[148:149]
	s_waitcnt lgkmcnt(0)
	v_lshl_add_u64 v[66:67], s[76:77], 0, v[68:69]
	v_lshl_add_u64 v[66:67], s[40:41], 3, v[66:67]
	global_store_dwordx2 v[66:67], v[64:65], off
.LBB0_835:
	s_or_b64 exec, exec, s[46:47]
	v_add_u32_e32 v64, 16, v148
	v_ashrrev_i32_e32 v65, 31, v64
	v_lshlrev_b64 v[70:71], 11, v[64:65]
	v_lshl_add_u64 v[70:71], s[44:45], 0, v[70:71]
	s_waitcnt lgkmcnt(0)
	v_cvt_pk_f16_f32 v66, v48, v49
	v_cvt_pk_f16_f32 v67, v50, v51
	v_cvt_pk_f16_f32 v68, v52, v53
	v_cvt_pk_f16_f32 v69, v54, v55
	v_lshl_add_u64 v[70:71], v[146:147], 1, v[70:71]
	global_store_dwordx4 v[70:71], v[66:69], off
	v_mul_f32_e32 v125, v48, v48
	v_mul_f32_e32 v127, v49, v49
	v_add_f32_e32 v66, v48, v49
	v_add_f32_e32 v68, v50, v51
	v_mul_f32_e32 v163, v50, v50
	v_mul_f32_e32 v165, v51, v51
	v_cvt_pk_f16_f32 v48, v112, v113
	v_cvt_pk_f16_f32 v49, v114, v115
	v_cvt_pk_f16_f32 v50, v116, v117
	v_cvt_pk_f16_f32 v51, v118, v119
	global_store_dwordx4 v[70:71], v[48:51], off offset:256
	v_add_f32_e32 v120, v52, v53
	v_add_f32_e32 v122, v54, v55
	v_pk_mul_f32 v[48:49], v[118:119], v[118:119]
	v_pk_mul_f32 v[50:51], v[116:117], v[116:117]
	v_mul_f32_e32 v167, v52, v52
	v_mul_f32_e32 v53, v53, v53
	v_mul_f32_e32 v169, v54, v54
	v_mul_f32_e32 v55, v55, v55
	v_pk_mov_b32 v[70:71], v[50:51], v[48:49] op_sel:[1,0]
	v_mov_b32_e32 v51, v49
	v_mov_b32_e32 v124, v112
	v_mov_b32_e32 v126, v113
	v_mov_b32_e32 v162, v114
	v_mov_b32_e32 v164, v115
	v_mov_b32_e32 v166, v116
	v_mov_b32_e32 v52, v117
	v_mov_b32_e32 v168, v118
	v_mov_b32_e32 v54, v119
	v_pk_add_f32 v[48:49], v[70:71], v[50:51]
	v_pk_add_f32 v[50:51], v[124:125], v[126:127]
	v_pk_add_f32 v[70:71], v[162:163], v[164:165]
	v_pk_add_f32 v[52:53], v[166:167], v[52:53]
	v_pk_add_f32 v[54:55], v[168:169], v[54:55]
	v_mul_f32_e32 v67, v112, v112
	v_mul_f32_e32 v69, v113, v113
	v_mul_f32_e32 v121, v114, v114
	v_mul_f32_e32 v123, v115, v115
	v_pk_add_f32 v[50:51], v[50:51], v[70:71]
	v_pk_add_f32 v[52:53], v[52:53], v[54:55]
	v_pk_add_f32 v[48:49], v[48:49], v[48:49] op_sel_hi:[0,1]
	v_pk_add_f32 v[50:51], v[50:51], v[52:53]
	v_pk_add_f32 v[52:53], v[66:67], v[68:69]
	v_pk_add_f32 v[54:55], v[120:121], v[122:123]
	v_mov_b32_e32 v137, v49
	v_pk_add_f32 v[52:53], v[52:53], v[54:55]
	s_nop 0
	v_pk_add_f32 v[48:49], v[52:53], v[136:137]
	s_nop 0
	v_pk_add_f32 v[48:49], v[50:51], v[48:49]
	s_nop 0
	v_mov_b32_e32 v50, v48
	v_mov_b32_e32 v51, v49
	s_nop 1
	v_permlane16_swap_b32 v50, v48
	v_permlane16_swap_b32 v51, v49
	s_nop 0
	s_nop 0
	v_pk_add_f32 v[48:49], v[48:49], v[50:51]
	s_nop 0
	v_mov_b32_e32 v50, v48
	v_mov_b32_e32 v51, v49
	s_nop 1
	v_permlane32_swap_b32 v50, v48
	v_permlane32_swap_b32 v51, v49
	s_nop 0
	v_pk_add_f32 v[48:49], v[48:49], v[50:51]
	s_and_saveexec_b64 s[46:47], vcc
	s_cbranch_execz .LBB0_837
	v_lshlrev_b64 v[52:53], 7, v[64:65]
	s_waitcnt lgkmcnt(0)
	v_lshl_add_u64 v[50:51], s[76:77], 0, v[52:53]
	v_lshl_add_u64 v[50:51], s[40:41], 3, v[50:51]
	global_store_dwordx2 v[50:51], v[48:49], off
.LBB0_837:
	s_or_b64 exec, exec, s[46:47]
	v_add_u32_e32 v48, 32, v148
	v_ashrrev_i32_e32 v49, 31, v48
	v_lshlrev_b64 v[54:55], 11, v[48:49]
	v_lshl_add_u64 v[54:55], s[44:45], 0, v[54:55]
	s_waitcnt lgkmcnt(0)
	v_cvt_pk_f16_f32 v50, v40, v41
	v_cvt_pk_f16_f32 v51, v42, v43
	v_cvt_pk_f16_f32 v52, v44, v45
	v_cvt_pk_f16_f32 v53, v46, v47
	v_lshl_add_u64 v[54:55], v[146:147], 1, v[54:55]
	global_store_dwordx4 v[54:55], v[50:53], off
	v_mul_f32_e32 v69, v40, v40
	v_mul_f32_e32 v71, v41, v41
	v_add_f32_e32 v50, v40, v41
	v_add_f32_e32 v52, v42, v43
	v_mul_f32_e32 v113, v42, v42
	v_mul_f32_e32 v115, v43, v43
	v_cvt_pk_f16_f32 v40, v104, v105
	v_cvt_pk_f16_f32 v41, v106, v107
	v_cvt_pk_f16_f32 v42, v108, v109
	v_cvt_pk_f16_f32 v43, v110, v111
	global_store_dwordx4 v[54:55], v[40:43], off offset:256
	v_add_f32_e32 v64, v44, v45
	v_add_f32_e32 v66, v46, v47
	v_pk_mul_f32 v[40:41], v[110:111], v[110:111]
	v_pk_mul_f32 v[42:43], v[108:109], v[108:109]
	v_mul_f32_e32 v117, v44, v44
	v_mul_f32_e32 v45, v45, v45
	v_mul_f32_e32 v119, v46, v46
	v_mul_f32_e32 v47, v47, v47
	v_pk_mov_b32 v[54:55], v[42:43], v[40:41] op_sel:[1,0]
	v_mov_b32_e32 v43, v41
	v_mov_b32_e32 v68, v104
	v_mov_b32_e32 v70, v105
	v_mov_b32_e32 v112, v106
	v_mov_b32_e32 v114, v107
	v_mov_b32_e32 v116, v108
	v_mov_b32_e32 v44, v109
	v_mov_b32_e32 v118, v110
	v_mov_b32_e32 v46, v111
	v_pk_add_f32 v[40:41], v[54:55], v[42:43]
	v_pk_add_f32 v[42:43], v[68:69], v[70:71]
	v_pk_add_f32 v[54:55], v[112:113], v[114:115]
	v_pk_add_f32 v[44:45], v[116:117], v[44:45]
	v_pk_add_f32 v[46:47], v[118:119], v[46:47]
	v_mul_f32_e32 v51, v104, v104
	v_mul_f32_e32 v53, v105, v105
	v_mul_f32_e32 v65, v106, v106
	v_mul_f32_e32 v67, v107, v107
	v_pk_add_f32 v[42:43], v[42:43], v[54:55]
	v_pk_add_f32 v[44:45], v[44:45], v[46:47]
	v_pk_add_f32 v[40:41], v[40:41], v[40:41] op_sel_hi:[0,1]
	v_pk_add_f32 v[42:43], v[42:43], v[44:45]
	v_pk_add_f32 v[44:45], v[50:51], v[52:53]
	v_pk_add_f32 v[46:47], v[64:65], v[66:67]
	v_mov_b32_e32 v137, v41
	v_pk_add_f32 v[44:45], v[44:45], v[46:47]
	s_nop 0
	v_pk_add_f32 v[40:41], v[44:45], v[136:137]
	s_nop 0
	v_pk_add_f32 v[40:41], v[42:43], v[40:41]
	s_nop 0
	v_mov_b32_e32 v42, v40
	v_mov_b32_e32 v43, v41
	s_nop 1
	v_permlane16_swap_b32 v42, v40
	v_permlane16_swap_b32 v43, v41
	s_nop 0
	s_nop 0
	v_pk_add_f32 v[40:41], v[40:41], v[42:43]
	s_nop 0
	v_mov_b32_e32 v42, v40
	v_mov_b32_e32 v43, v41
	s_nop 1
	v_permlane32_swap_b32 v42, v40
	v_permlane32_swap_b32 v43, v41
	s_nop 0
	v_pk_add_f32 v[40:41], v[40:41], v[42:43]
	s_and_saveexec_b64 s[46:47], vcc
	s_cbranch_execz .LBB0_839
	v_lshlrev_b64 v[44:45], 7, v[48:49]
	s_waitcnt lgkmcnt(0)
	v_lshl_add_u64 v[42:43], s[76:77], 0, v[44:45]
	v_lshl_add_u64 v[42:43], s[40:41], 3, v[42:43]
	global_store_dwordx2 v[42:43], v[40:41], off
.LBB0_839:
	s_or_b64 exec, exec, s[46:47]
	v_add_u32_e32 v40, 48, v148
	v_ashrrev_i32_e32 v41, 31, v40
	v_lshlrev_b64 v[46:47], 11, v[40:41]
	v_lshl_add_u64 v[46:47], s[44:45], 0, v[46:47]
	s_waitcnt lgkmcnt(0)
	v_cvt_pk_f16_f32 v42, v32, v33
	v_cvt_pk_f16_f32 v43, v34, v35
	v_cvt_pk_f16_f32 v44, v36, v37
	v_cvt_pk_f16_f32 v45, v38, v39
	v_lshl_add_u64 v[46:47], v[146:147], 1, v[46:47]
	global_store_dwordx4 v[46:47], v[42:45], off
	v_mul_f32_e32 v53, v32, v32
	v_mul_f32_e32 v55, v33, v33
	v_add_f32_e32 v42, v32, v33
	v_add_f32_e32 v44, v34, v35
	v_mul_f32_e32 v65, v34, v34
	v_mul_f32_e32 v67, v35, v35
	v_cvt_pk_f16_f32 v32, v96, v97
	v_cvt_pk_f16_f32 v33, v98, v99
	v_cvt_pk_f16_f32 v34, v100, v101
	v_cvt_pk_f16_f32 v35, v102, v103
	global_store_dwordx4 v[46:47], v[32:35], off offset:256
	v_add_f32_e32 v48, v36, v37
	v_add_f32_e32 v50, v38, v39
	v_pk_mul_f32 v[32:33], v[102:103], v[102:103]
	v_pk_mul_f32 v[34:35], v[100:101], v[100:101]
	v_mul_f32_e32 v69, v36, v36
	v_mul_f32_e32 v37, v37, v37
	v_mul_f32_e32 v71, v38, v38
	v_mul_f32_e32 v39, v39, v39
	v_pk_mov_b32 v[46:47], v[34:35], v[32:33] op_sel:[1,0]
	v_mov_b32_e32 v35, v33
	v_mov_b32_e32 v52, v96
	v_mov_b32_e32 v54, v97
	v_mov_b32_e32 v64, v98
	v_mov_b32_e32 v66, v99
	v_mov_b32_e32 v68, v100
	v_mov_b32_e32 v36, v101
	v_mov_b32_e32 v70, v102
	v_mov_b32_e32 v38, v103
	v_pk_add_f32 v[32:33], v[46:47], v[34:35]
	v_pk_add_f32 v[34:35], v[52:53], v[54:55]
	v_pk_add_f32 v[46:47], v[64:65], v[66:67]
	v_pk_add_f32 v[36:37], v[68:69], v[36:37]
	v_pk_add_f32 v[38:39], v[70:71], v[38:39]
	v_mul_f32_e32 v43, v96, v96
	v_mul_f32_e32 v45, v97, v97
	v_mul_f32_e32 v49, v98, v98
	v_mul_f32_e32 v51, v99, v99
	v_pk_add_f32 v[34:35], v[34:35], v[46:47]
	v_pk_add_f32 v[36:37], v[36:37], v[38:39]
	v_pk_add_f32 v[32:33], v[32:33], v[32:33] op_sel_hi:[0,1]
	v_pk_add_f32 v[34:35], v[34:35], v[36:37]
	v_pk_add_f32 v[36:37], v[42:43], v[44:45]
	v_pk_add_f32 v[38:39], v[48:49], v[50:51]
	v_mov_b32_e32 v137, v33
	v_pk_add_f32 v[36:37], v[36:37], v[38:39]
	s_nop 0
	v_pk_add_f32 v[32:33], v[36:37], v[136:137]
	s_nop 0
	v_pk_add_f32 v[32:33], v[34:35], v[32:33]
	s_nop 0
	v_mov_b32_e32 v34, v32
	v_mov_b32_e32 v35, v33
	s_nop 1
	v_permlane16_swap_b32 v34, v32
	v_permlane16_swap_b32 v35, v33
	s_nop 0
	s_nop 0
	v_pk_add_f32 v[32:33], v[32:33], v[34:35]
	s_nop 0
	v_mov_b32_e32 v34, v32
	v_mov_b32_e32 v35, v33
	s_nop 1
	v_permlane32_swap_b32 v34, v32
	v_permlane32_swap_b32 v35, v33
	s_nop 0
	v_pk_add_f32 v[32:33], v[32:33], v[34:35]
	s_and_saveexec_b64 s[46:47], vcc
	s_cbranch_execz .LBB0_841
	v_lshlrev_b64 v[36:37], 7, v[40:41]
	s_waitcnt lgkmcnt(0)
	v_lshl_add_u64 v[34:35], s[76:77], 0, v[36:37]
	v_lshl_add_u64 v[34:35], s[40:41], 3, v[34:35]
	global_store_dwordx2 v[34:35], v[32:33], off
.LBB0_841:
	s_or_b64 exec, exec, s[46:47]
	v_add_u32_e32 v32, 0x80, v148
	v_ashrrev_i32_e32 v33, 31, v32
	v_lshlrev_b64 v[38:39], 11, v[32:33]
	v_lshl_add_u64 v[38:39], s[44:45], 0, v[38:39]
	s_waitcnt lgkmcnt(0)
	v_cvt_pk_f16_f32 v34, v24, v25
	v_cvt_pk_f16_f32 v35, v26, v27
	v_cvt_pk_f16_f32 v36, v28, v29
	v_cvt_pk_f16_f32 v37, v30, v31
	v_lshl_add_u64 v[38:39], v[146:147], 1, v[38:39]
	global_store_dwordx4 v[38:39], v[34:37], off
	v_mul_f32_e32 v45, v24, v24
	v_mul_f32_e32 v47, v25, v25
	v_add_f32_e32 v34, v24, v25
	v_add_f32_e32 v36, v26, v27
	v_mul_f32_e32 v49, v26, v26
	v_mul_f32_e32 v51, v27, v27
	v_cvt_pk_f16_f32 v24, v80, v81
	v_cvt_pk_f16_f32 v25, v82, v83
	v_cvt_pk_f16_f32 v26, v84, v85
	v_cvt_pk_f16_f32 v27, v86, v87
	global_store_dwordx4 v[38:39], v[24:27], off offset:256
	v_add_f32_e32 v40, v28, v29
	v_add_f32_e32 v42, v30, v31
	v_pk_mul_f32 v[24:25], v[86:87], v[86:87]
	v_pk_mul_f32 v[26:27], v[84:85], v[84:85]
	v_mul_f32_e32 v53, v28, v28
	v_mul_f32_e32 v29, v29, v29
	v_mul_f32_e32 v55, v30, v30
	v_mul_f32_e32 v31, v31, v31
	v_pk_mov_b32 v[38:39], v[26:27], v[24:25] op_sel:[1,0]
	v_mov_b32_e32 v27, v25
	v_mov_b32_e32 v44, v80
	v_mov_b32_e32 v46, v81
	v_mov_b32_e32 v48, v82
	v_mov_b32_e32 v50, v83
	v_mov_b32_e32 v52, v84
	v_mov_b32_e32 v28, v85
	v_mov_b32_e32 v54, v86
	v_mov_b32_e32 v30, v87
	v_pk_add_f32 v[24:25], v[38:39], v[26:27]
	v_pk_add_f32 v[26:27], v[44:45], v[46:47]
	v_pk_add_f32 v[38:39], v[48:49], v[50:51]
	v_pk_add_f32 v[28:29], v[52:53], v[28:29]
	v_pk_add_f32 v[30:31], v[54:55], v[30:31]
	v_mul_f32_e32 v35, v80, v80
	v_mul_f32_e32 v37, v81, v81
	v_mul_f32_e32 v41, v82, v82
	v_mul_f32_e32 v43, v83, v83
	v_pk_add_f32 v[26:27], v[26:27], v[38:39]
	v_pk_add_f32 v[28:29], v[28:29], v[30:31]
	v_pk_add_f32 v[24:25], v[24:25], v[24:25] op_sel_hi:[0,1]
	v_pk_add_f32 v[26:27], v[26:27], v[28:29]
	v_pk_add_f32 v[28:29], v[34:35], v[36:37]
	v_pk_add_f32 v[30:31], v[40:41], v[42:43]
	v_mov_b32_e32 v137, v25
	v_pk_add_f32 v[28:29], v[28:29], v[30:31]
	s_nop 0
	v_pk_add_f32 v[24:25], v[28:29], v[136:137]
	s_nop 0
	v_pk_add_f32 v[24:25], v[26:27], v[24:25]
	s_nop 0
	v_mov_b32_e32 v26, v24
	v_mov_b32_e32 v27, v25
	s_nop 1
	v_permlane16_swap_b32 v26, v24
	v_permlane16_swap_b32 v27, v25
	s_nop 0
	s_nop 0
	v_pk_add_f32 v[24:25], v[24:25], v[26:27]
	s_nop 0
	v_mov_b32_e32 v26, v24
	v_mov_b32_e32 v27, v25
	s_nop 1
	v_permlane32_swap_b32 v26, v24
	v_permlane32_swap_b32 v27, v25
	s_nop 0
	v_pk_add_f32 v[24:25], v[24:25], v[26:27]
	s_and_saveexec_b64 s[46:47], vcc
	s_cbranch_execz .LBB0_843
	v_lshlrev_b64 v[28:29], 7, v[32:33]
	s_waitcnt lgkmcnt(0)
	v_lshl_add_u64 v[26:27], s[76:77], 0, v[28:29]
	v_lshl_add_u64 v[26:27], s[40:41], 3, v[26:27]
	global_store_dwordx2 v[26:27], v[24:25], off
.LBB0_843:
	s_or_b64 exec, exec, s[46:47]
	v_add_u32_e32 v24, 0x90, v148
	v_ashrrev_i32_e32 v25, 31, v24
	v_lshlrev_b64 v[30:31], 11, v[24:25]
	v_lshl_add_u64 v[30:31], s[44:45], 0, v[30:31]
	s_waitcnt lgkmcnt(0)
	v_cvt_pk_f16_f32 v26, v16, v17
	v_cvt_pk_f16_f32 v27, v18, v19
	v_cvt_pk_f16_f32 v28, v20, v21
	v_cvt_pk_f16_f32 v29, v22, v23
	v_lshl_add_u64 v[30:31], v[146:147], 1, v[30:31]
	global_store_dwordx4 v[30:31], v[26:29], off
	v_mul_f32_e32 v37, v16, v16
	v_mul_f32_e32 v39, v17, v17
	v_add_f32_e32 v26, v16, v17
	v_add_f32_e32 v28, v18, v19
	v_mul_f32_e32 v41, v18, v18
	v_mul_f32_e32 v43, v19, v19
	v_cvt_pk_f16_f32 v16, v88, v89
	v_cvt_pk_f16_f32 v17, v90, v91
	v_cvt_pk_f16_f32 v18, v92, v93
	v_cvt_pk_f16_f32 v19, v94, v95
	global_store_dwordx4 v[30:31], v[16:19], off offset:256
	v_add_f32_e32 v32, v20, v21
	v_add_f32_e32 v34, v22, v23
	v_pk_mul_f32 v[16:17], v[94:95], v[94:95]
	v_pk_mul_f32 v[18:19], v[92:93], v[92:93]
	v_mul_f32_e32 v45, v20, v20
	v_mul_f32_e32 v21, v21, v21
	v_mul_f32_e32 v47, v22, v22
	v_mul_f32_e32 v23, v23, v23
	v_pk_mov_b32 v[30:31], v[18:19], v[16:17] op_sel:[1,0]
	v_mov_b32_e32 v19, v17
	v_mov_b32_e32 v36, v88
	v_mov_b32_e32 v38, v89
	v_mov_b32_e32 v40, v90
	v_mov_b32_e32 v42, v91
	v_mov_b32_e32 v44, v92
	v_mov_b32_e32 v20, v93
	v_mov_b32_e32 v46, v94
	v_mov_b32_e32 v22, v95
	v_pk_add_f32 v[16:17], v[30:31], v[18:19]
	v_pk_add_f32 v[18:19], v[36:37], v[38:39]
	v_pk_add_f32 v[30:31], v[40:41], v[42:43]
	v_pk_add_f32 v[20:21], v[44:45], v[20:21]
	v_pk_add_f32 v[22:23], v[46:47], v[22:23]
	v_mul_f32_e32 v27, v88, v88
	v_mul_f32_e32 v29, v89, v89
	v_mul_f32_e32 v33, v90, v90
	v_mul_f32_e32 v35, v91, v91
	v_pk_add_f32 v[18:19], v[18:19], v[30:31]
	v_pk_add_f32 v[20:21], v[20:21], v[22:23]
	v_pk_add_f32 v[16:17], v[16:17], v[16:17] op_sel_hi:[0,1]
	v_pk_add_f32 v[18:19], v[18:19], v[20:21]
	v_pk_add_f32 v[20:21], v[26:27], v[28:29]
	v_pk_add_f32 v[22:23], v[32:33], v[34:35]
	v_mov_b32_e32 v137, v17
	v_pk_add_f32 v[20:21], v[20:21], v[22:23]
	s_nop 0
	v_pk_add_f32 v[16:17], v[20:21], v[136:137]
	s_nop 0
	v_pk_add_f32 v[16:17], v[18:19], v[16:17]
	s_nop 0
	v_mov_b32_e32 v18, v16
	v_mov_b32_e32 v19, v17
	s_nop 1
	v_permlane16_swap_b32 v18, v16
	v_permlane16_swap_b32 v19, v17
	s_nop 0
	s_nop 0
	v_pk_add_f32 v[16:17], v[16:17], v[18:19]
	s_nop 0
	v_mov_b32_e32 v18, v16
	v_mov_b32_e32 v19, v17
	s_nop 1
	v_permlane32_swap_b32 v18, v16
	v_permlane32_swap_b32 v19, v17
	s_nop 0
	v_pk_add_f32 v[16:17], v[16:17], v[18:19]
	s_and_saveexec_b64 s[46:47], vcc
	s_cbranch_execz .LBB0_845
	v_lshlrev_b64 v[20:21], 7, v[24:25]
	s_waitcnt lgkmcnt(0)
	v_lshl_add_u64 v[18:19], s[76:77], 0, v[20:21]
	v_lshl_add_u64 v[18:19], s[40:41], 3, v[18:19]
	global_store_dwordx2 v[18:19], v[16:17], off
.LBB0_845:
	s_or_b64 exec, exec, s[46:47]
	v_add_u32_e32 v16, 0xa0, v148
	v_ashrrev_i32_e32 v17, 31, v16
	v_lshlrev_b64 v[22:23], 11, v[16:17]
	v_lshl_add_u64 v[22:23], s[44:45], 0, v[22:23]
	s_waitcnt lgkmcnt(0)
	v_cvt_pk_f16_f32 v18, v8, v9
	v_cvt_pk_f16_f32 v19, v10, v11
	v_cvt_pk_f16_f32 v20, v12, v13
	v_cvt_pk_f16_f32 v21, v14, v15
	v_lshl_add_u64 v[22:23], v[146:147], 1, v[22:23]
	global_store_dwordx4 v[22:23], v[18:21], off
	v_mul_f32_e32 v29, v8, v8
	v_mul_f32_e32 v31, v9, v9
	v_add_f32_e32 v18, v8, v9
	v_add_f32_e32 v20, v10, v11
	v_mul_f32_e32 v33, v10, v10
	v_mul_f32_e32 v35, v11, v11
	v_cvt_pk_f16_f32 v8, v72, v73
	v_cvt_pk_f16_f32 v9, v74, v75
	v_cvt_pk_f16_f32 v10, v76, v77
	v_cvt_pk_f16_f32 v11, v78, v79
	global_store_dwordx4 v[22:23], v[8:11], off offset:256
	v_add_f32_e32 v24, v12, v13
	v_add_f32_e32 v26, v14, v15
	v_pk_mul_f32 v[8:9], v[78:79], v[78:79]
	v_pk_mul_f32 v[10:11], v[76:77], v[76:77]
	v_mul_f32_e32 v37, v12, v12
	v_mul_f32_e32 v13, v13, v13
	v_mul_f32_e32 v39, v14, v14
	v_mul_f32_e32 v15, v15, v15
	v_pk_mov_b32 v[22:23], v[10:11], v[8:9] op_sel:[1,0]
	v_mov_b32_e32 v11, v9
	v_mov_b32_e32 v28, v72
	v_mov_b32_e32 v30, v73
	v_mov_b32_e32 v32, v74
	v_mov_b32_e32 v34, v75
	v_mov_b32_e32 v36, v76
	v_mov_b32_e32 v12, v77
	v_mov_b32_e32 v38, v78
	v_mov_b32_e32 v14, v79
	v_pk_add_f32 v[8:9], v[22:23], v[10:11]
	v_pk_add_f32 v[10:11], v[28:29], v[30:31]
	v_pk_add_f32 v[22:23], v[32:33], v[34:35]
	v_pk_add_f32 v[12:13], v[36:37], v[12:13]
	v_pk_add_f32 v[14:15], v[38:39], v[14:15]
	v_mul_f32_e32 v19, v72, v72
	v_mul_f32_e32 v21, v73, v73
	v_mul_f32_e32 v25, v74, v74
	v_mul_f32_e32 v27, v75, v75
	v_pk_add_f32 v[10:11], v[10:11], v[22:23]
	v_pk_add_f32 v[12:13], v[12:13], v[14:15]
	v_pk_add_f32 v[8:9], v[8:9], v[8:9] op_sel_hi:[0,1]
	v_pk_add_f32 v[10:11], v[10:11], v[12:13]
	v_pk_add_f32 v[12:13], v[18:19], v[20:21]
	v_pk_add_f32 v[14:15], v[24:25], v[26:27]
	v_mov_b32_e32 v137, v9
	v_pk_add_f32 v[12:13], v[12:13], v[14:15]
	s_nop 0
	v_pk_add_f32 v[8:9], v[12:13], v[136:137]
	s_nop 0
	v_pk_add_f32 v[8:9], v[10:11], v[8:9]
	s_nop 0
	v_mov_b32_e32 v10, v8
	v_mov_b32_e32 v11, v9
	s_nop 1
	v_permlane16_swap_b32 v10, v8
	v_permlane16_swap_b32 v11, v9
	s_nop 0
	s_nop 0
	v_pk_add_f32 v[8:9], v[8:9], v[10:11]
	s_nop 0
	v_mov_b32_e32 v10, v8
	v_mov_b32_e32 v11, v9
	s_nop 1
	v_permlane32_swap_b32 v10, v8
	v_permlane32_swap_b32 v11, v9
	s_nop 0
	v_pk_add_f32 v[8:9], v[8:9], v[10:11]
	s_and_saveexec_b64 s[46:47], vcc
	s_cbranch_execz .LBB0_847
	v_lshlrev_b64 v[12:13], 7, v[16:17]
	s_waitcnt lgkmcnt(0)
	v_lshl_add_u64 v[10:11], s[76:77], 0, v[12:13]
	v_lshl_add_u64 v[10:11], s[40:41], 3, v[10:11]
	global_store_dwordx2 v[10:11], v[8:9], off
.LBB0_847:
	s_or_b64 exec, exec, s[46:47]
	v_add_u32_e32 v8, 0xb0, v148
	v_ashrrev_i32_e32 v9, 31, v8
	v_lshlrev_b64 v[14:15], 11, v[8:9]
	v_lshl_add_u64 v[14:15], s[44:45], 0, v[14:15]
	s_waitcnt lgkmcnt(0)
	v_cvt_pk_f16_f32 v10, v0, v1
	v_cvt_pk_f16_f32 v11, v2, v3
	v_cvt_pk_f16_f32 v12, v4, v5
	v_cvt_pk_f16_f32 v13, v6, v7
	v_lshl_add_u64 v[14:15], v[146:147], 1, v[14:15]
	global_store_dwordx4 v[14:15], v[10:13], off
	v_mul_f32_e32 v21, v0, v0
	v_mul_f32_e32 v23, v1, v1
	v_add_f32_e32 v10, v0, v1
	v_add_f32_e32 v12, v2, v3
	v_mul_f32_e32 v25, v2, v2
	v_mul_f32_e32 v27, v3, v3
	v_cvt_pk_f16_f32 v0, v56, v57
	v_cvt_pk_f16_f32 v1, v58, v59
	v_cvt_pk_f16_f32 v2, v60, v61
	v_cvt_pk_f16_f32 v3, v62, v63
	global_store_dwordx4 v[14:15], v[0:3], off offset:256
	v_add_f32_e32 v16, v4, v5
	v_add_f32_e32 v18, v6, v7
	v_pk_mul_f32 v[0:1], v[62:63], v[62:63]
	v_pk_mul_f32 v[2:3], v[60:61], v[60:61]
	v_mul_f32_e32 v29, v4, v4
	v_mul_f32_e32 v5, v5, v5
	v_mul_f32_e32 v31, v6, v6
	v_mul_f32_e32 v7, v7, v7
	v_pk_mov_b32 v[14:15], v[2:3], v[0:1] op_sel:[1,0]
	v_mov_b32_e32 v3, v1
	v_mov_b32_e32 v20, v56
	v_mov_b32_e32 v22, v57
	v_mov_b32_e32 v24, v58
	v_mov_b32_e32 v26, v59
	v_mov_b32_e32 v28, v60
	v_mov_b32_e32 v4, v61
	v_mov_b32_e32 v30, v62
	v_mov_b32_e32 v6, v63
	v_pk_add_f32 v[0:1], v[14:15], v[2:3]
	v_pk_add_f32 v[2:3], v[20:21], v[22:23]
	v_pk_add_f32 v[14:15], v[24:25], v[26:27]
	v_pk_add_f32 v[4:5], v[28:29], v[4:5]
	v_pk_add_f32 v[6:7], v[30:31], v[6:7]
	v_mul_f32_e32 v11, v56, v56
	v_mul_f32_e32 v13, v57, v57
	v_mul_f32_e32 v17, v58, v58
	v_mul_f32_e32 v19, v59, v59
	v_pk_add_f32 v[2:3], v[2:3], v[14:15]
	v_pk_add_f32 v[4:5], v[4:5], v[6:7]
	v_pk_add_f32 v[0:1], v[0:1], v[0:1] op_sel_hi:[0,1]
	v_pk_add_f32 v[2:3], v[2:3], v[4:5]
	v_pk_add_f32 v[4:5], v[10:11], v[12:13]
	v_pk_add_f32 v[6:7], v[16:17], v[18:19]
	v_mov_b32_e32 v137, v1
	v_pk_add_f32 v[4:5], v[4:5], v[6:7]
	s_nop 0
	v_pk_add_f32 v[0:1], v[4:5], v[136:137]
	s_nop 0
	v_pk_add_f32 v[0:1], v[2:3], v[0:1]
	s_nop 0
	v_mov_b32_e32 v2, v0
	v_mov_b32_e32 v3, v1
	s_nop 1
	v_permlane16_swap_b32 v2, v0
	v_permlane16_swap_b32 v3, v1
	s_nop 0
	s_nop 0
	v_pk_add_f32 v[0:1], v[0:1], v[2:3]
	s_nop 0
	v_mov_b32_e32 v2, v0
	v_mov_b32_e32 v3, v1
	s_nop 1
	v_permlane32_swap_b32 v2, v0
	v_permlane32_swap_b32 v3, v1
	s_nop 0
	v_pk_add_f32 v[0:1], v[0:1], v[2:3]
	s_and_saveexec_b64 s[46:47], vcc
	s_cbranch_execz .LBB0_849
	v_lshlrev_b64 v[4:5], 7, v[8:9]
	s_waitcnt lgkmcnt(0)
	v_lshl_add_u64 v[2:3], s[76:77], 0, v[4:5]
	v_lshl_add_u64 v[2:3], s[40:41], 3, v[2:3]
	global_store_dwordx2 v[2:3], v[0:1], off

.LBB0_1516:
	s_lshl_b32 s35, s92, 8
	v_mov_b32_e32 v137, v151
	v_mov_b32_e32 v146, v153
	s_add_i32 s35, s35, s11
	v_cvt_pk_f16_f32 v162, v64, v65
	v_add_u32_e32 v148, s35, v146
	s_lshl_b32 s35, s88, 8
	s_or_b32 s35, s35, s66
	v_ashrrev_i32_e32 v149, 31, v148
	v_lshl_add_u32 v146, v137, 3, s35
	v_lshlrev_b64 v[166:167], 11, v[148:149]
	v_ashrrev_i32_e32 v147, 31, v146
	v_lshl_add_u64 v[166:167], s[44:45], 0, v[166:167]
	v_cvt_pk_f16_f32 v163, v66, v67
	v_cvt_pk_f16_f32 v164, v68, v69
	v_cvt_pk_f16_f32 v165, v70, v71
	v_lshl_add_u64 v[166:167], v[146:147], 1, v[166:167]
	global_store_dwordx4 v[166:167], v[162:165], off
	v_mul_f32_e32 v173, v64, v64
	v_mul_f32_e32 v175, v65, v65
	v_add_f32_e32 v162, v64, v65
	v_add_f32_e32 v164, v66, v67
	v_mul_f32_e32 v177, v66, v66
	v_mul_f32_e32 v179, v67, v67
	v_cvt_pk_f16_f32 v64, v120, v121
	v_cvt_pk_f16_f32 v65, v122, v123
	v_cvt_pk_f16_f32 v66, v124, v125
	v_cvt_pk_f16_f32 v67, v126, v127
	global_store_dwordx4 v[166:167], v[64:67], off offset:256
	v_add_f32_e32 v168, v68, v69
	v_add_f32_e32 v170, v70, v71
	v_pk_mul_f32 v[64:65], v[126:127], v[126:127]
	v_pk_mul_f32 v[66:67], v[124:125], v[124:125]
	v_mul_f32_e32 v181, v68, v68
	v_mul_f32_e32 v69, v69, v69
	v_mul_f32_e32 v183, v70, v70
	v_mul_f32_e32 v71, v71, v71
	v_pk_mov_b32 v[166:167], v[66:67], v[64:65] op_sel:[1,0]
	v_mov_b32_e32 v67, v65
	v_mov_b32_e32 v172, v120
	v_mov_b32_e32 v174, v121
	v_mov_b32_e32 v176, v122
	v_mov_b32_e32 v178, v123
	v_mov_b32_e32 v180, v124
	v_mov_b32_e32 v68, v125
	v_mov_b32_e32 v182, v126
	v_mov_b32_e32 v70, v127
	v_mul_f32_e32 v163, v120, v120
	v_mul_f32_e32 v165, v121, v121
	v_pk_add_f32 v[64:65], v[166:167], v[66:67]
	v_pk_add_f32 v[66:67], v[172:173], v[174:175]
	v_pk_add_f32 v[120:121], v[176:177], v[178:179]
	v_pk_add_f32 v[68:69], v[180:181], v[68:69]
	v_pk_add_f32 v[70:71], v[182:183], v[70:71]
	v_mul_f32_e32 v169, v122, v122
	v_mul_f32_e32 v171, v123, v123
	v_pk_add_f32 v[66:67], v[66:67], v[120:121]
	v_pk_add_f32 v[68:69], v[68:69], v[70:71]
	v_pk_add_f32 v[64:65], v[64:65], v[64:65] op_sel_hi:[0,1]
	v_pk_add_f32 v[66:67], v[66:67], v[68:69]
	v_pk_add_f32 v[68:69], v[162:163], v[164:165]
	v_pk_add_f32 v[70:71], v[168:169], v[170:171]
	v_cmp_eq_u32_e32 vcc, 0, v137
	v_pk_add_f32 v[68:69], v[68:69], v[70:71]
	v_mov_b32_e32 v137, v65
	v_pk_add_f32 v[64:65], v[68:69], v[136:137]
	s_lshl_b32 s40, s88, 2
	v_pk_add_f32 v[64:65], v[66:67], v[64:65]
	s_nop 0
	v_mov_b32_e32 v66, v64
	v_mov_b32_e32 v67, v65
	s_nop 1
	v_permlane16_swap_b32 v66, v64
	v_permlane16_swap_b32 v67, v65
	s_nop 0
	s_ashr_i32 s41, s40, 31
	s_or_b64 s[40:41], s[40:41], s[0:1]
	s_nop 0
	v_pk_add_f32 v[64:65], v[64:65], v[66:67]
	s_nop 0
	v_mov_b32_e32 v66, v64
	v_mov_b32_e32 v67, v65
	s_nop 1
	v_permlane32_swap_b32 v66, v64
	v_permlane32_swap_b32 v67, v65
	s_nop 0
	v_pk_add_f32 v[64:65], v[64:65], v[66:67]
	s_and_saveexec_b64 s[46:47], vcc
	s_cbranch_execz .LBB0_1518
	v_lshlrev_b64 v[68:69], 7, v[148:149]
	s_waitcnt lgkmcnt(0)
	v_lshl_add_u64 v[66:67], s[62:63], 0, v[68:69]
	v_lshl_add_u64 v[66:67], s[40:41], 3, v[66:67]
	global_store_dwordx2 v[66:67], v[64:65], off
.LBB0_1518:
	s_or_b64 exec, exec, s[46:47]
	v_add_u32_e32 v64, 16, v148
	v_ashrrev_i32_e32 v65, 31, v64
	v_lshlrev_b64 v[70:71], 11, v[64:65]
	v_lshl_add_u64 v[70:71], s[44:45], 0, v[70:71]
	s_waitcnt lgkmcnt(0)
	v_cvt_pk_f16_f32 v66, v48, v49
	v_cvt_pk_f16_f32 v67, v50, v51
	v_cvt_pk_f16_f32 v68, v52, v53
	v_cvt_pk_f16_f32 v69, v54, v55
	v_lshl_add_u64 v[70:71], v[146:147], 1, v[70:71]
	global_store_dwordx4 v[70:71], v[66:69], off
	v_mul_f32_e32 v125, v48, v48
	v_mul_f32_e32 v127, v49, v49
	v_add_f32_e32 v66, v48, v49
	v_add_f32_e32 v68, v50, v51
	v_mul_f32_e32 v163, v50, v50
	v_mul_f32_e32 v165, v51, v51
	v_cvt_pk_f16_f32 v48, v112, v113
	v_cvt_pk_f16_f32 v49, v114, v115
	v_cvt_pk_f16_f32 v50, v116, v117
	v_cvt_pk_f16_f32 v51, v118, v119
	global_store_dwordx4 v[70:71], v[48:51], off offset:256
	v_add_f32_e32 v120, v52, v53
	v_add_f32_e32 v122, v54, v55
	v_pk_mul_f32 v[48:49], v[118:119], v[118:119]
	v_pk_mul_f32 v[50:51], v[116:117], v[116:117]
	v_mul_f32_e32 v167, v52, v52
	v_mul_f32_e32 v53, v53, v53
	v_mul_f32_e32 v169, v54, v54
	v_mul_f32_e32 v55, v55, v55
	v_pk_mov_b32 v[70:71], v[50:51], v[48:49] op_sel:[1,0]
	v_mov_b32_e32 v51, v49
	v_mov_b32_e32 v124, v112
	v_mov_b32_e32 v126, v113
	v_mov_b32_e32 v162, v114
	v_mov_b32_e32 v164, v115
	v_mov_b32_e32 v166, v116
	v_mov_b32_e32 v52, v117
	v_mov_b32_e32 v168, v118
	v_mov_b32_e32 v54, v119
	v_pk_add_f32 v[48:49], v[70:71], v[50:51]
	v_pk_add_f32 v[50:51], v[124:125], v[126:127]
	v_pk_add_f32 v[70:71], v[162:163], v[164:165]
	v_pk_add_f32 v[52:53], v[166:167], v[52:53]
	v_pk_add_f32 v[54:55], v[168:169], v[54:55]
	v_mul_f32_e32 v67, v112, v112
	v_mul_f32_e32 v69, v113, v113
	v_mul_f32_e32 v121, v114, v114
	v_mul_f32_e32 v123, v115, v115
	v_pk_add_f32 v[50:51], v[50:51], v[70:71]
	v_pk_add_f32 v[52:53], v[52:53], v[54:55]
	v_pk_add_f32 v[48:49], v[48:49], v[48:49] op_sel_hi:[0,1]
	v_pk_add_f32 v[50:51], v[50:51], v[52:53]
	v_pk_add_f32 v[52:53], v[66:67], v[68:69]
	v_pk_add_f32 v[54:55], v[120:121], v[122:123]
	v_mov_b32_e32 v137, v49
	v_pk_add_f32 v[52:53], v[52:53], v[54:55]
	s_nop 0
	v_pk_add_f32 v[48:49], v[52:53], v[136:137]
	s_nop 0
	v_pk_add_f32 v[48:49], v[50:51], v[48:49]
	s_nop 0
	v_mov_b32_e32 v50, v48
	v_mov_b32_e32 v51, v49
	s_nop 1
	v_permlane16_swap_b32 v50, v48
	v_permlane16_swap_b32 v51, v49
	s_nop 0
	s_nop 0
	v_pk_add_f32 v[48:49], v[48:49], v[50:51]
	s_nop 0
	v_mov_b32_e32 v50, v48
	v_mov_b32_e32 v51, v49
	s_nop 1
	v_permlane32_swap_b32 v50, v48
	v_permlane32_swap_b32 v51, v49
	s_nop 0
	v_pk_add_f32 v[48:49], v[48:49], v[50:51]
	s_and_saveexec_b64 s[46:47], vcc
	s_cbranch_execz .LBB0_1520
	v_lshlrev_b64 v[52:53], 7, v[64:65]
	s_waitcnt lgkmcnt(0)
	v_lshl_add_u64 v[50:51], s[62:63], 0, v[52:53]
	v_lshl_add_u64 v[50:51], s[40:41], 3, v[50:51]
	global_store_dwordx2 v[50:51], v[48:49], off
.LBB0_1520:
	s_or_b64 exec, exec, s[46:47]
	v_add_u32_e32 v48, 32, v148
	v_ashrrev_i32_e32 v49, 31, v48
	v_lshlrev_b64 v[54:55], 11, v[48:49]
	v_lshl_add_u64 v[54:55], s[44:45], 0, v[54:55]
	s_waitcnt lgkmcnt(0)
	v_cvt_pk_f16_f32 v50, v40, v41
	v_cvt_pk_f16_f32 v51, v42, v43
	v_cvt_pk_f16_f32 v52, v44, v45
	v_cvt_pk_f16_f32 v53, v46, v47
	v_lshl_add_u64 v[54:55], v[146:147], 1, v[54:55]
	global_store_dwordx4 v[54:55], v[50:53], off
	v_mul_f32_e32 v69, v40, v40
	v_mul_f32_e32 v71, v41, v41
	v_add_f32_e32 v50, v40, v41
	v_add_f32_e32 v52, v42, v43
	v_mul_f32_e32 v113, v42, v42
	v_mul_f32_e32 v115, v43, v43
	v_cvt_pk_f16_f32 v40, v104, v105
	v_cvt_pk_f16_f32 v41, v106, v107
	v_cvt_pk_f16_f32 v42, v108, v109
	v_cvt_pk_f16_f32 v43, v110, v111
	global_store_dwordx4 v[54:55], v[40:43], off offset:256
	v_add_f32_e32 v64, v44, v45
	v_add_f32_e32 v66, v46, v47
	v_pk_mul_f32 v[40:41], v[110:111], v[110:111]
	v_pk_mul_f32 v[42:43], v[108:109], v[108:109]
	v_mul_f32_e32 v117, v44, v44
	v_mul_f32_e32 v45, v45, v45
	v_mul_f32_e32 v119, v46, v46
	v_mul_f32_e32 v47, v47, v47
	v_pk_mov_b32 v[54:55], v[42:43], v[40:41] op_sel:[1,0]
	v_mov_b32_e32 v43, v41
	v_mov_b32_e32 v68, v104
	v_mov_b32_e32 v70, v105
	v_mov_b32_e32 v112, v106
	v_mov_b32_e32 v114, v107
	v_mov_b32_e32 v116, v108
	v_mov_b32_e32 v44, v109
	v_mov_b32_e32 v118, v110
	v_mov_b32_e32 v46, v111
	v_pk_add_f32 v[40:41], v[54:55], v[42:43]
	v_pk_add_f32 v[42:43], v[68:69], v[70:71]
	v_pk_add_f32 v[54:55], v[112:113], v[114:115]
	v_pk_add_f32 v[44:45], v[116:117], v[44:45]
	v_pk_add_f32 v[46:47], v[118:119], v[46:47]
	v_mul_f32_e32 v51, v104, v104
	v_mul_f32_e32 v53, v105, v105
	v_mul_f32_e32 v65, v106, v106
	v_mul_f32_e32 v67, v107, v107
	v_pk_add_f32 v[42:43], v[42:43], v[54:55]
	v_pk_add_f32 v[44:45], v[44:45], v[46:47]
	v_pk_add_f32 v[40:41], v[40:41], v[40:41] op_sel_hi:[0,1]
	v_pk_add_f32 v[42:43], v[42:43], v[44:45]
	v_pk_add_f32 v[44:45], v[50:51], v[52:53]
	v_pk_add_f32 v[46:47], v[64:65], v[66:67]
	v_mov_b32_e32 v137, v41
	v_pk_add_f32 v[44:45], v[44:45], v[46:47]
	s_nop 0
	v_pk_add_f32 v[40:41], v[44:45], v[136:137]
	s_nop 0
	v_pk_add_f32 v[40:41], v[42:43], v[40:41]
	s_nop 0
	v_mov_b32_e32 v42, v40
	v_mov_b32_e32 v43, v41
	s_nop 1
	v_permlane16_swap_b32 v42, v40
	v_permlane16_swap_b32 v43, v41
	s_nop 0
	s_nop 0
	v_pk_add_f32 v[40:41], v[40:41], v[42:43]
	s_nop 0
	v_mov_b32_e32 v42, v40
	v_mov_b32_e32 v43, v41
	s_nop 1
	v_permlane32_swap_b32 v42, v40
	v_permlane32_swap_b32 v43, v41
	s_nop 0
	v_pk_add_f32 v[40:41], v[40:41], v[42:43]
	s_and_saveexec_b64 s[46:47], vcc
	s_cbranch_execz .LBB0_1522
	v_lshlrev_b64 v[44:45], 7, v[48:49]
	s_waitcnt lgkmcnt(0)
	v_lshl_add_u64 v[42:43], s[62:63], 0, v[44:45]
	v_lshl_add_u64 v[42:43], s[40:41], 3, v[42:43]
	global_store_dwordx2 v[42:43], v[40:41], off
.LBB0_1522:
	s_or_b64 exec, exec, s[46:47]
	v_add_u32_e32 v40, 48, v148
	v_ashrrev_i32_e32 v41, 31, v40
	v_lshlrev_b64 v[46:47], 11, v[40:41]
	v_lshl_add_u64 v[46:47], s[44:45], 0, v[46:47]
	s_waitcnt lgkmcnt(0)
	v_cvt_pk_f16_f32 v42, v32, v33
	v_cvt_pk_f16_f32 v43, v34, v35
	v_cvt_pk_f16_f32 v44, v36, v37
	v_cvt_pk_f16_f32 v45, v38, v39
	v_lshl_add_u64 v[46:47], v[146:147], 1, v[46:47]
	global_store_dwordx4 v[46:47], v[42:45], off
	v_mul_f32_e32 v53, v32, v32
	v_mul_f32_e32 v55, v33, v33
	v_add_f32_e32 v42, v32, v33
	v_add_f32_e32 v44, v34, v35
	v_mul_f32_e32 v65, v34, v34
	v_mul_f32_e32 v67, v35, v35
	v_cvt_pk_f16_f32 v32, v96, v97
	v_cvt_pk_f16_f32 v33, v98, v99
	v_cvt_pk_f16_f32 v34, v100, v101
	v_cvt_pk_f16_f32 v35, v102, v103
	global_store_dwordx4 v[46:47], v[32:35], off offset:256
	v_add_f32_e32 v48, v36, v37
	v_add_f32_e32 v50, v38, v39
	v_pk_mul_f32 v[32:33], v[102:103], v[102:103]
	v_pk_mul_f32 v[34:35], v[100:101], v[100:101]
	v_mul_f32_e32 v69, v36, v36
	v_mul_f32_e32 v37, v37, v37
	v_mul_f32_e32 v71, v38, v38
	v_mul_f32_e32 v39, v39, v39
	v_pk_mov_b32 v[46:47], v[34:35], v[32:33] op_sel:[1,0]
	v_mov_b32_e32 v35, v33
	v_mov_b32_e32 v52, v96
	v_mov_b32_e32 v54, v97
	v_mov_b32_e32 v64, v98
	v_mov_b32_e32 v66, v99
	v_mov_b32_e32 v68, v100
	v_mov_b32_e32 v36, v101
	v_mov_b32_e32 v70, v102
	v_mov_b32_e32 v38, v103
	v_pk_add_f32 v[32:33], v[46:47], v[34:35]
	v_pk_add_f32 v[34:35], v[52:53], v[54:55]
	v_pk_add_f32 v[46:47], v[64:65], v[66:67]
	v_pk_add_f32 v[36:37], v[68:69], v[36:37]
	v_pk_add_f32 v[38:39], v[70:71], v[38:39]
	v_mul_f32_e32 v43, v96, v96
	v_mul_f32_e32 v45, v97, v97
	v_mul_f32_e32 v49, v98, v98
	v_mul_f32_e32 v51, v99, v99
	v_pk_add_f32 v[34:35], v[34:35], v[46:47]
	v_pk_add_f32 v[36:37], v[36:37], v[38:39]
	v_pk_add_f32 v[32:33], v[32:33], v[32:33] op_sel_hi:[0,1]
	v_pk_add_f32 v[34:35], v[34:35], v[36:37]
	v_pk_add_f32 v[36:37], v[42:43], v[44:45]
	v_pk_add_f32 v[38:39], v[48:49], v[50:51]
	v_mov_b32_e32 v137, v33
	v_pk_add_f32 v[36:37], v[36:37], v[38:39]
	s_nop 0
	v_pk_add_f32 v[32:33], v[36:37], v[136:137]
	s_nop 0
	v_pk_add_f32 v[32:33], v[34:35], v[32:33]
	s_nop 0
	v_mov_b32_e32 v34, v32
	v_mov_b32_e32 v35, v33
	s_nop 1
	v_permlane16_swap_b32 v34, v32
	v_permlane16_swap_b32 v35, v33
	s_nop 0
	s_nop 0
	v_pk_add_f32 v[32:33], v[32:33], v[34:35]
	s_nop 0
	v_mov_b32_e32 v34, v32
	v_mov_b32_e32 v35, v33
	s_nop 1
	v_permlane32_swap_b32 v34, v32
	v_permlane32_swap_b32 v35, v33
	s_nop 0
	v_pk_add_f32 v[32:33], v[32:33], v[34:35]
	s_and_saveexec_b64 s[46:47], vcc
	s_cbranch_execz .LBB0_1524
	v_lshlrev_b64 v[36:37], 7, v[40:41]
	s_waitcnt lgkmcnt(0)
	v_lshl_add_u64 v[34:35], s[62:63], 0, v[36:37]
	v_lshl_add_u64 v[34:35], s[40:41], 3, v[34:35]
	global_store_dwordx2 v[34:35], v[32:33], off
.LBB0_1524:
	s_or_b64 exec, exec, s[46:47]
	v_add_u32_e32 v32, 0x80, v148
	v_ashrrev_i32_e32 v33, 31, v32
	v_lshlrev_b64 v[38:39], 11, v[32:33]
	v_lshl_add_u64 v[38:39], s[44:45], 0, v[38:39]
	s_waitcnt lgkmcnt(0)
	v_cvt_pk_f16_f32 v34, v24, v25
	v_cvt_pk_f16_f32 v35, v26, v27
	v_cvt_pk_f16_f32 v36, v28, v29
	v_cvt_pk_f16_f32 v37, v30, v31
	v_lshl_add_u64 v[38:39], v[146:147], 1, v[38:39]
	global_store_dwordx4 v[38:39], v[34:37], off
	v_mul_f32_e32 v45, v24, v24
	v_mul_f32_e32 v47, v25, v25
	v_add_f32_e32 v34, v24, v25
	v_add_f32_e32 v36, v26, v27
	v_mul_f32_e32 v49, v26, v26
	v_mul_f32_e32 v51, v27, v27
	v_cvt_pk_f16_f32 v24, v80, v81
	v_cvt_pk_f16_f32 v25, v82, v83
	v_cvt_pk_f16_f32 v26, v84, v85
	v_cvt_pk_f16_f32 v27, v86, v87
	global_store_dwordx4 v[38:39], v[24:27], off offset:256
	v_add_f32_e32 v40, v28, v29
	v_add_f32_e32 v42, v30, v31
	v_pk_mul_f32 v[24:25], v[86:87], v[86:87]
	v_pk_mul_f32 v[26:27], v[84:85], v[84:85]
	v_mul_f32_e32 v53, v28, v28
	v_mul_f32_e32 v29, v29, v29
	v_mul_f32_e32 v55, v30, v30
	v_mul_f32_e32 v31, v31, v31
	v_pk_mov_b32 v[38:39], v[26:27], v[24:25] op_sel:[1,0]
	v_mov_b32_e32 v27, v25
	v_mov_b32_e32 v44, v80
	v_mov_b32_e32 v46, v81
	v_mov_b32_e32 v48, v82
	v_mov_b32_e32 v50, v83
	v_mov_b32_e32 v52, v84
	v_mov_b32_e32 v28, v85
	v_mov_b32_e32 v54, v86
	v_mov_b32_e32 v30, v87
	v_pk_add_f32 v[24:25], v[38:39], v[26:27]
	v_pk_add_f32 v[26:27], v[44:45], v[46:47]
	v_pk_add_f32 v[38:39], v[48:49], v[50:51]
	v_pk_add_f32 v[28:29], v[52:53], v[28:29]
	v_pk_add_f32 v[30:31], v[54:55], v[30:31]
	v_mul_f32_e32 v35, v80, v80
	v_mul_f32_e32 v37, v81, v81
	v_mul_f32_e32 v41, v82, v82
	v_mul_f32_e32 v43, v83, v83
	v_pk_add_f32 v[26:27], v[26:27], v[38:39]
	v_pk_add_f32 v[28:29], v[28:29], v[30:31]
	v_pk_add_f32 v[24:25], v[24:25], v[24:25] op_sel_hi:[0,1]
	v_pk_add_f32 v[26:27], v[26:27], v[28:29]
	v_pk_add_f32 v[28:29], v[34:35], v[36:37]
	v_pk_add_f32 v[30:31], v[40:41], v[42:43]
	v_mov_b32_e32 v137, v25
	v_pk_add_f32 v[28:29], v[28:29], v[30:31]
	s_nop 0
	v_pk_add_f32 v[24:25], v[28:29], v[136:137]
	s_nop 0
	v_pk_add_f32 v[24:25], v[26:27], v[24:25]
	s_nop 0
	v_mov_b32_e32 v26, v24
	v_mov_b32_e32 v27, v25
	s_nop 1
	v_permlane16_swap_b32 v26, v24
	v_permlane16_swap_b32 v27, v25
	s_nop 0
	s_nop 0
	v_pk_add_f32 v[24:25], v[24:25], v[26:27]
	s_nop 0
	v_mov_b32_e32 v26, v24
	v_mov_b32_e32 v27, v25
	s_nop 1
	v_permlane32_swap_b32 v26, v24
	v_permlane32_swap_b32 v27, v25
	s_nop 0
	v_pk_add_f32 v[24:25], v[24:25], v[26:27]
	s_and_saveexec_b64 s[46:47], vcc
	s_cbranch_execz .LBB0_1526
	v_lshlrev_b64 v[28:29], 7, v[32:33]
	s_waitcnt lgkmcnt(0)
	v_lshl_add_u64 v[26:27], s[62:63], 0, v[28:29]
	v_lshl_add_u64 v[26:27], s[40:41], 3, v[26:27]
	global_store_dwordx2 v[26:27], v[24:25], off
.LBB0_1526:
	s_or_b64 exec, exec, s[46:47]
	v_add_u32_e32 v24, 0x90, v148
	v_ashrrev_i32_e32 v25, 31, v24
	v_lshlrev_b64 v[30:31], 11, v[24:25]
	v_lshl_add_u64 v[30:31], s[44:45], 0, v[30:31]
	s_waitcnt lgkmcnt(0)
	v_cvt_pk_f16_f32 v26, v16, v17
	v_cvt_pk_f16_f32 v27, v18, v19
	v_cvt_pk_f16_f32 v28, v20, v21
	v_cvt_pk_f16_f32 v29, v22, v23
	v_lshl_add_u64 v[30:31], v[146:147], 1, v[30:31]
	global_store_dwordx4 v[30:31], v[26:29], off
	v_mul_f32_e32 v37, v16, v16
	v_mul_f32_e32 v39, v17, v17
	v_add_f32_e32 v26, v16, v17
	v_add_f32_e32 v28, v18, v19
	v_mul_f32_e32 v41, v18, v18
	v_mul_f32_e32 v43, v19, v19
	v_cvt_pk_f16_f32 v16, v88, v89
	v_cvt_pk_f16_f32 v17, v90, v91
	v_cvt_pk_f16_f32 v18, v92, v93
	v_cvt_pk_f16_f32 v19, v94, v95
	global_store_dwordx4 v[30:31], v[16:19], off offset:256
	v_add_f32_e32 v32, v20, v21
	v_add_f32_e32 v34, v22, v23
	v_pk_mul_f32 v[16:17], v[94:95], v[94:95]
	v_pk_mul_f32 v[18:19], v[92:93], v[92:93]
	v_mul_f32_e32 v45, v20, v20
	v_mul_f32_e32 v21, v21, v21
	v_mul_f32_e32 v47, v22, v22
	v_mul_f32_e32 v23, v23, v23
	v_pk_mov_b32 v[30:31], v[18:19], v[16:17] op_sel:[1,0]
	v_mov_b32_e32 v19, v17
	v_mov_b32_e32 v36, v88
	v_mov_b32_e32 v38, v89
	v_mov_b32_e32 v40, v90
	v_mov_b32_e32 v42, v91
	v_mov_b32_e32 v44, v92
	v_mov_b32_e32 v20, v93
	v_mov_b32_e32 v46, v94
	v_mov_b32_e32 v22, v95
	v_pk_add_f32 v[16:17], v[30:31], v[18:19]
	v_pk_add_f32 v[18:19], v[36:37], v[38:39]
	v_pk_add_f32 v[30:31], v[40:41], v[42:43]
	v_pk_add_f32 v[20:21], v[44:45], v[20:21]
	v_pk_add_f32 v[22:23], v[46:47], v[22:23]
	v_mul_f32_e32 v27, v88, v88
	v_mul_f32_e32 v29, v89, v89
	v_mul_f32_e32 v33, v90, v90
	v_mul_f32_e32 v35, v91, v91
	v_pk_add_f32 v[18:19], v[18:19], v[30:31]
	v_pk_add_f32 v[20:21], v[20:21], v[22:23]
	v_pk_add_f32 v[16:17], v[16:17], v[16:17] op_sel_hi:[0,1]
	v_pk_add_f32 v[18:19], v[18:19], v[20:21]
	v_pk_add_f32 v[20:21], v[26:27], v[28:29]
	v_pk_add_f32 v[22:23], v[32:33], v[34:35]
	v_mov_b32_e32 v137, v17
	v_pk_add_f32 v[20:21], v[20:21], v[22:23]
	s_nop 0
	v_pk_add_f32 v[16:17], v[20:21], v[136:137]
	s_nop 0
	v_pk_add_f32 v[16:17], v[18:19], v[16:17]
	s_nop 0
	v_mov_b32_e32 v18, v16
	v_mov_b32_e32 v19, v17
	s_nop 1
	v_permlane16_swap_b32 v18, v16
	v_permlane16_swap_b32 v19, v17
	s_nop 0
	s_nop 0
	v_pk_add_f32 v[16:17], v[16:17], v[18:19]
	s_nop 0
	v_mov_b32_e32 v18, v16
	v_mov_b32_e32 v19, v17
	s_nop 1
	v_permlane32_swap_b32 v18, v16
	v_permlane32_swap_b32 v19, v17
	s_nop 0
	v_pk_add_f32 v[16:17], v[16:17], v[18:19]
	s_and_saveexec_b64 s[46:47], vcc
	s_cbranch_execz .LBB0_1528
	v_lshlrev_b64 v[20:21], 7, v[24:25]
	s_waitcnt lgkmcnt(0)
	v_lshl_add_u64 v[18:19], s[62:63], 0, v[20:21]
	v_lshl_add_u64 v[18:19], s[40:41], 3, v[18:19]
	global_store_dwordx2 v[18:19], v[16:17], off
.LBB0_1528:
	s_or_b64 exec, exec, s[46:47]
	v_add_u32_e32 v16, 0xa0, v148
	v_ashrrev_i32_e32 v17, 31, v16
	v_lshlrev_b64 v[22:23], 11, v[16:17]
	v_lshl_add_u64 v[22:23], s[44:45], 0, v[22:23]
	s_waitcnt lgkmcnt(0)
	v_cvt_pk_f16_f32 v18, v8, v9
	v_cvt_pk_f16_f32 v19, v10, v11
	v_cvt_pk_f16_f32 v20, v12, v13
	v_cvt_pk_f16_f32 v21, v14, v15
	v_lshl_add_u64 v[22:23], v[146:147], 1, v[22:23]
	global_store_dwordx4 v[22:23], v[18:21], off
	v_mul_f32_e32 v29, v8, v8
	v_mul_f32_e32 v31, v9, v9
	v_add_f32_e32 v18, v8, v9
	v_add_f32_e32 v20, v10, v11
	v_mul_f32_e32 v33, v10, v10
	v_mul_f32_e32 v35, v11, v11
	v_cvt_pk_f16_f32 v8, v72, v73
	v_cvt_pk_f16_f32 v9, v74, v75
	v_cvt_pk_f16_f32 v10, v76, v77
	v_cvt_pk_f16_f32 v11, v78, v79
	global_store_dwordx4 v[22:23], v[8:11], off offset:256
	v_add_f32_e32 v24, v12, v13
	v_add_f32_e32 v26, v14, v15
	v_pk_mul_f32 v[8:9], v[78:79], v[78:79]
	v_pk_mul_f32 v[10:11], v[76:77], v[76:77]
	v_mul_f32_e32 v37, v12, v12
	v_mul_f32_e32 v13, v13, v13
	v_mul_f32_e32 v39, v14, v14
	v_mul_f32_e32 v15, v15, v15
	v_pk_mov_b32 v[22:23], v[10:11], v[8:9] op_sel:[1,0]
	v_mov_b32_e32 v11, v9
	v_mov_b32_e32 v28, v72
	v_mov_b32_e32 v30, v73
	v_mov_b32_e32 v32, v74
	v_mov_b32_e32 v34, v75
	v_mov_b32_e32 v36, v76
	v_mov_b32_e32 v12, v77
	v_mov_b32_e32 v38, v78
	v_mov_b32_e32 v14, v79
	v_pk_add_f32 v[8:9], v[22:23], v[10:11]
	v_pk_add_f32 v[10:11], v[28:29], v[30:31]
	v_pk_add_f32 v[22:23], v[32:33], v[34:35]
	v_pk_add_f32 v[12:13], v[36:37], v[12:13]
	v_pk_add_f32 v[14:15], v[38:39], v[14:15]
	v_mul_f32_e32 v19, v72, v72
	v_mul_f32_e32 v21, v73, v73
	v_mul_f32_e32 v25, v74, v74
	v_mul_f32_e32 v27, v75, v75
	v_pk_add_f32 v[10:11], v[10:11], v[22:23]
	v_pk_add_f32 v[12:13], v[12:13], v[14:15]
	v_pk_add_f32 v[8:9], v[8:9], v[8:9] op_sel_hi:[0,1]
	v_pk_add_f32 v[10:11], v[10:11], v[12:13]
	v_pk_add_f32 v[12:13], v[18:19], v[20:21]
	v_pk_add_f32 v[14:15], v[24:25], v[26:27]
	v_mov_b32_e32 v137, v9
	v_pk_add_f32 v[12:13], v[12:13], v[14:15]
	s_nop 0
	v_pk_add_f32 v[8:9], v[12:13], v[136:137]
	s_nop 0
	v_pk_add_f32 v[8:9], v[10:11], v[8:9]
	s_nop 0
	v_mov_b32_e32 v10, v8
	v_mov_b32_e32 v11, v9
	s_nop 1
	v_permlane16_swap_b32 v10, v8
	v_permlane16_swap_b32 v11, v9
	s_nop 0
	s_nop 0
	v_pk_add_f32 v[8:9], v[8:9], v[10:11]
	s_nop 0
	v_mov_b32_e32 v10, v8
	v_mov_b32_e32 v11, v9
	s_nop 1
	v_permlane32_swap_b32 v10, v8
	v_permlane32_swap_b32 v11, v9
	s_nop 0
	v_pk_add_f32 v[8:9], v[8:9], v[10:11]
	s_and_saveexec_b64 s[46:47], vcc
	s_cbranch_execz .LBB0_1530
	v_lshlrev_b64 v[12:13], 7, v[16:17]
	s_waitcnt lgkmcnt(0)
	v_lshl_add_u64 v[10:11], s[62:63], 0, v[12:13]
	v_lshl_add_u64 v[10:11], s[40:41], 3, v[10:11]
	global_store_dwordx2 v[10:11], v[8:9], off
.LBB0_1530:
	s_or_b64 exec, exec, s[46:47]
	v_add_u32_e32 v8, 0xb0, v148
	v_ashrrev_i32_e32 v9, 31, v8
	v_lshlrev_b64 v[14:15], 11, v[8:9]
	v_lshl_add_u64 v[14:15], s[44:45], 0, v[14:15]
	s_waitcnt lgkmcnt(0)
	v_cvt_pk_f16_f32 v10, v0, v1
	v_cvt_pk_f16_f32 v11, v2, v3
	v_cvt_pk_f16_f32 v12, v4, v5
	v_cvt_pk_f16_f32 v13, v6, v7
	v_lshl_add_u64 v[14:15], v[146:147], 1, v[14:15]
	global_store_dwordx4 v[14:15], v[10:13], off
	v_mul_f32_e32 v21, v0, v0
	v_mul_f32_e32 v23, v1, v1
	v_add_f32_e32 v10, v0, v1
	v_add_f32_e32 v12, v2, v3
	v_mul_f32_e32 v25, v2, v2
	v_mul_f32_e32 v27, v3, v3
	v_cvt_pk_f16_f32 v0, v56, v57
	v_cvt_pk_f16_f32 v1, v58, v59
	v_cvt_pk_f16_f32 v2, v60, v61
	v_cvt_pk_f16_f32 v3, v62, v63
	global_store_dwordx4 v[14:15], v[0:3], off offset:256
	v_add_f32_e32 v16, v4, v5
	v_add_f32_e32 v18, v6, v7
	v_pk_mul_f32 v[0:1], v[62:63], v[62:63]
	v_pk_mul_f32 v[2:3], v[60:61], v[60:61]
	v_mul_f32_e32 v29, v4, v4
	v_mul_f32_e32 v5, v5, v5
	v_mul_f32_e32 v31, v6, v6
	v_mul_f32_e32 v7, v7, v7
	v_pk_mov_b32 v[14:15], v[2:3], v[0:1] op_sel:[1,0]
	v_mov_b32_e32 v3, v1
	v_mov_b32_e32 v20, v56
	v_mov_b32_e32 v22, v57
	v_mov_b32_e32 v24, v58
	v_mov_b32_e32 v26, v59
	v_mov_b32_e32 v28, v60
	v_mov_b32_e32 v4, v61
	v_mov_b32_e32 v30, v62
	v_mov_b32_e32 v6, v63
	v_pk_add_f32 v[0:1], v[14:15], v[2:3]
	v_pk_add_f32 v[2:3], v[20:21], v[22:23]
	v_pk_add_f32 v[14:15], v[24:25], v[26:27]
	v_pk_add_f32 v[4:5], v[28:29], v[4:5]
	v_pk_add_f32 v[6:7], v[30:31], v[6:7]
	v_mul_f32_e32 v11, v56, v56
	v_mul_f32_e32 v13, v57, v57
	v_mul_f32_e32 v17, v58, v58
	v_mul_f32_e32 v19, v59, v59
	v_pk_add_f32 v[2:3], v[2:3], v[14:15]
	v_pk_add_f32 v[4:5], v[4:5], v[6:7]
	v_pk_add_f32 v[0:1], v[0:1], v[0:1] op_sel_hi:[0,1]
	v_pk_add_f32 v[2:3], v[2:3], v[4:5]
	v_pk_add_f32 v[4:5], v[10:11], v[12:13]
	v_pk_add_f32 v[6:7], v[16:17], v[18:19]
	v_mov_b32_e32 v137, v1
	v_pk_add_f32 v[4:5], v[4:5], v[6:7]
	s_nop 0
	v_pk_add_f32 v[0:1], v[4:5], v[136:137]
	s_nop 0
	v_pk_add_f32 v[0:1], v[2:3], v[0:1]
	s_nop 0
	v_mov_b32_e32 v2, v0
	v_mov_b32_e32 v3, v1
	s_nop 1
	v_permlane16_swap_b32 v2, v0
	v_permlane16_swap_b32 v3, v1
	s_nop 0
	s_nop 0
	v_pk_add_f32 v[0:1], v[0:1], v[2:3]
	s_nop 0
	v_mov_b32_e32 v2, v0
	v_mov_b32_e32 v3, v1
	s_nop 1
	v_permlane32_swap_b32 v2, v0
	v_permlane32_swap_b32 v3, v1
	s_nop 0
	v_pk_add_f32 v[0:1], v[0:1], v[2:3]
	s_and_saveexec_b64 s[46:47], vcc
	s_cbranch_execz .LBB0_1532
	v_lshlrev_b64 v[4:5], 7, v[8:9]
	s_waitcnt lgkmcnt(0)
	v_lshl_add_u64 v[2:3], s[62:63], 0, v[4:5]
	v_lshl_add_u64 v[2:3], s[40:41], 3, v[2:3]
	global_store_dwordx2 v[2:3], v[0:1], off

.LBB0_1693:
	s_lshl_b32 s40, s80, 8
	v_mov_b32_e32 v137, v153
	v_mov_b32_e32 v149, v151
	s_add_i32 s40, s40, s15
	v_cvt_pk_f16_f32 v162, v64, v65
	v_add_u32_e32 v148, s40, v137
	s_lshl_b32 s40, s79, 8
	s_or_b32 s40, s40, s66
	v_lshl_add_u32 v146, v149, 3, s40
	v_cmp_eq_u32_e32 vcc, 0, v149
	v_ashrrev_i32_e32 v149, 31, v148
	v_lshlrev_b64 v[166:167], 11, v[148:149]
	v_ashrrev_i32_e32 v147, 31, v146
	v_lshl_add_u64 v[166:167], s[44:45], 0, v[166:167]
	v_cvt_pk_f16_f32 v163, v66, v67
	v_cvt_pk_f16_f32 v164, v68, v69
	v_cvt_pk_f16_f32 v165, v70, v71
	v_lshl_add_u64 v[166:167], v[146:147], 1, v[166:167]
	global_store_dwordx4 v[166:167], v[162:165], off
	v_mul_f32_e32 v173, v64, v64
	v_mul_f32_e32 v175, v65, v65
	v_add_f32_e32 v162, v64, v65
	v_add_f32_e32 v164, v66, v67
	v_mul_f32_e32 v177, v66, v66
	v_mul_f32_e32 v179, v67, v67
	v_cvt_pk_f16_f32 v64, v120, v121
	v_cvt_pk_f16_f32 v65, v122, v123
	v_cvt_pk_f16_f32 v66, v124, v125
	v_cvt_pk_f16_f32 v67, v126, v127
	global_store_dwordx4 v[166:167], v[64:67], off offset:256
	v_add_f32_e32 v168, v68, v69
	v_add_f32_e32 v170, v70, v71
	v_pk_mul_f32 v[64:65], v[126:127], v[126:127]
	v_pk_mul_f32 v[66:67], v[124:125], v[124:125]
	v_mul_f32_e32 v181, v68, v68
	v_mul_f32_e32 v69, v69, v69
	v_mul_f32_e32 v183, v70, v70
	v_mul_f32_e32 v71, v71, v71
	v_pk_mov_b32 v[166:167], v[66:67], v[64:65] op_sel:[1,0]
	v_mov_b32_e32 v67, v65
	v_mov_b32_e32 v172, v120
	v_mov_b32_e32 v174, v121
	v_mov_b32_e32 v176, v122
	v_mov_b32_e32 v178, v123
	v_mov_b32_e32 v180, v124
	v_mov_b32_e32 v68, v125
	v_mov_b32_e32 v182, v126
	v_mov_b32_e32 v70, v127
	v_mul_f32_e32 v163, v120, v120
	v_mul_f32_e32 v165, v121, v121
	v_pk_add_f32 v[64:65], v[166:167], v[66:67]
	v_pk_add_f32 v[66:67], v[172:173], v[174:175]
	v_pk_add_f32 v[120:121], v[176:177], v[178:179]
	v_pk_add_f32 v[68:69], v[180:181], v[68:69]
	v_pk_add_f32 v[70:71], v[182:183], v[70:71]
	v_mul_f32_e32 v169, v122, v122
	v_mul_f32_e32 v171, v123, v123
	v_pk_add_f32 v[66:67], v[66:67], v[120:121]
	v_pk_add_f32 v[68:69], v[68:69], v[70:71]
	v_pk_add_f32 v[64:65], v[64:65], v[64:65] op_sel_hi:[0,1]
	v_pk_add_f32 v[66:67], v[66:67], v[68:69]
	v_pk_add_f32 v[68:69], v[162:163], v[164:165]
	v_pk_add_f32 v[70:71], v[168:169], v[170:171]
	v_mov_b32_e32 v137, v65
	v_pk_add_f32 v[68:69], v[68:69], v[70:71]
	s_lshl_b32 s40, s79, 2
	v_pk_add_f32 v[64:65], v[68:69], v[136:137]
	s_ashr_i32 s41, s40, 31
	v_pk_add_f32 v[64:65], v[66:67], v[64:65]
	s_nop 0
	v_mov_b32_e32 v66, v64
	v_mov_b32_e32 v67, v65
	s_nop 1
	v_permlane16_swap_b32 v66, v64
	v_permlane16_swap_b32 v67, v65
	s_nop 0
	s_or_b64 s[40:41], s[40:41], s[4:5]
	s_nop 0
	v_pk_add_f32 v[64:65], v[64:65], v[66:67]
	s_nop 0
	v_mov_b32_e32 v66, v64
	v_mov_b32_e32 v67, v65
	s_nop 1
	v_permlane32_swap_b32 v66, v64
	v_permlane32_swap_b32 v67, v65
	s_nop 0
	v_pk_add_f32 v[64:65], v[64:65], v[66:67]
	s_and_saveexec_b64 s[46:47], vcc
	s_cbranch_execz .LBB0_1695
	v_lshlrev_b64 v[68:69], 7, v[148:149]
	s_waitcnt lgkmcnt(0)
	v_lshl_add_u64 v[66:67], s[76:77], 0, v[68:69]
	v_lshl_add_u64 v[66:67], s[40:41], 3, v[66:67]
	global_store_dwordx2 v[66:67], v[64:65], off

.LBB0_2377:
	s_lshl_b32 s37, s96, 8
	v_mov_b32_e32 v137, v153
	v_mov_b32_e32 v149, v151
	s_add_i32 s37, s37, s13
	v_cvt_pk_f16_f32 v162, v64, v65
	v_add_u32_e32 v148, s37, v137
	s_lshl_b32 s37, s94, 8
	s_or_b32 s37, s37, s66
	v_lshl_add_u32 v146, v149, 3, s37
	v_cmp_eq_u32_e32 vcc, 0, v149
	v_ashrrev_i32_e32 v149, 31, v148
	v_lshlrev_b64 v[166:167], 11, v[148:149]
	v_ashrrev_i32_e32 v147, 31, v146
	v_lshl_add_u64 v[166:167], s[44:45], 0, v[166:167]
	v_cvt_pk_f16_f32 v163, v66, v67
	v_cvt_pk_f16_f32 v164, v68, v69
	v_cvt_pk_f16_f32 v165, v70, v71
	v_lshl_add_u64 v[166:167], v[146:147], 1, v[166:167]
	global_store_dwordx4 v[166:167], v[162:165], off
	v_mul_f32_e32 v173, v64, v64
	v_mul_f32_e32 v175, v65, v65
	v_add_f32_e32 v162, v64, v65
	v_add_f32_e32 v164, v66, v67
	v_mul_f32_e32 v177, v66, v66
	v_mul_f32_e32 v179, v67, v67
	v_cvt_pk_f16_f32 v64, v120, v121
	v_cvt_pk_f16_f32 v65, v122, v123
	v_cvt_pk_f16_f32 v66, v124, v125
	v_cvt_pk_f16_f32 v67, v126, v127
	global_store_dwordx4 v[166:167], v[64:67], off offset:256
	v_add_f32_e32 v168, v68, v69
	v_add_f32_e32 v170, v70, v71
	v_pk_mul_f32 v[64:65], v[126:127], v[126:127]
	v_pk_mul_f32 v[66:67], v[124:125], v[124:125]
	v_mul_f32_e32 v181, v68, v68
	v_mul_f32_e32 v69, v69, v69
	v_mul_f32_e32 v183, v70, v70
	v_mul_f32_e32 v71, v71, v71
	v_pk_mov_b32 v[166:167], v[66:67], v[64:65] op_sel:[1,0]
	v_mov_b32_e32 v67, v65
	v_mov_b32_e32 v172, v120
	v_mov_b32_e32 v174, v121
	v_mov_b32_e32 v176, v122
	v_mov_b32_e32 v178, v123
	v_mov_b32_e32 v180, v124
	v_mov_b32_e32 v68, v125
	v_mov_b32_e32 v182, v126
	v_mov_b32_e32 v70, v127
	v_mul_f32_e32 v163, v120, v120
	v_mul_f32_e32 v165, v121, v121
	v_pk_add_f32 v[64:65], v[166:167], v[66:67]
	v_pk_add_f32 v[66:67], v[172:173], v[174:175]
	v_pk_add_f32 v[120:121], v[176:177], v[178:179]
	v_pk_add_f32 v[68:69], v[180:181], v[68:69]
	v_pk_add_f32 v[70:71], v[182:183], v[70:71]
	v_mul_f32_e32 v169, v122, v122
	v_mul_f32_e32 v171, v123, v123
	v_pk_add_f32 v[66:67], v[66:67], v[120:121]
	v_pk_add_f32 v[68:69], v[68:69], v[70:71]
	v_pk_add_f32 v[64:65], v[64:65], v[64:65] op_sel_hi:[0,1]
	v_pk_add_f32 v[66:67], v[66:67], v[68:69]
	v_pk_add_f32 v[68:69], v[162:163], v[164:165]
	v_pk_add_f32 v[70:71], v[168:169], v[170:171]
	v_mov_b32_e32 v137, v65
	v_pk_add_f32 v[68:69], v[68:69], v[70:71]
	s_lshl_b32 s40, s94, 2
	v_pk_add_f32 v[64:65], v[68:69], v[136:137]
	s_ashr_i32 s41, s40, 31
	v_pk_add_f32 v[64:65], v[66:67], v[64:65]
	s_nop 0
	v_mov_b32_e32 v66, v64
	v_mov_b32_e32 v67, v65
	s_nop 1
	v_permlane16_swap_b32 v66, v64
	v_permlane16_swap_b32 v67, v65
	s_nop 0
	s_or_b64 s[40:41], s[40:41], s[4:5]
	s_nop 0
	v_pk_add_f32 v[64:65], v[64:65], v[66:67]
	s_nop 0
	v_mov_b32_e32 v66, v64
	v_mov_b32_e32 v67, v65
	s_nop 1
	v_permlane32_swap_b32 v66, v64
	v_permlane32_swap_b32 v67, v65
	s_nop 0
	v_pk_add_f32 v[64:65], v[64:65], v[66:67]
	s_and_saveexec_b64 s[46:47], vcc
	s_cbranch_execz .LBB0_2379
	v_lshlrev_b64 v[68:69], 7, v[148:149]
	s_waitcnt lgkmcnt(0)
	v_lshl_add_u64 v[66:67], s[62:63], 0, v[68:69]
	v_lshl_add_u64 v[66:67], s[40:41], 3, v[66:67]
	global_store_dwordx2 v[66:67], v[64:65], off
